# v40 + all remaining s_setprio removed from the GEMM K-loops (x3 phase probe: 5441 vs 5455 us)
# speedup vs baseline: 1.0076x; 1.0076x over previous
; #define PG8_STAGE(bufoff, gbase, voff) do { _Pragma("unroll") for (int _i = 0; _i < 2; ++_i) \
;         __builtin_amdgcn_global_load_lds((const unsigned*)((const char*)(gbase) + (voff)[_i]), (PG8_LAS unsigned*)(lds + (bufoff) + ldsw + _i * 8192), 16, 0, 0); } while (0)
; #define PG8_WAIT_V(n) asm volatile("s_waitcnt vmcnt(" #n ")" ::: "memory")
; #define PG8_WAIT_L(n) asm volatile("s_waitcnt lgkmcnt(" #n ")" ::: "memory")
; #define PG8_BAR __builtin_amdgcn_s_barrier()
; #define PG8_SCHED __builtin_amdgcn_sched_barrier(0)
;     ...
;             const char* a1 = cA + (size_t)(t + 1) * kstep;
;             const char* a2 = last ? nA : cA + (size_t)(t + 2) * kstep; const char* b2 = last ? nB : cB + (size_t)(t + 2) * kstep;
;             const char* a3 = a2 + kstep; const char* b3 = b2 + kstep;
;             if (last && has_next) S.a_ready(nxt);
;             if (last) E.pre(pre, cur, wr, fr);
;             if constexpr (MIDK > 0) { if (t == MIDK / BK) E.mid(acc, cur, wr, wc, fr, fq); }
;             if constexpr (SP2) {
;             PG8_LDB(B0, 0, 0); PG8_LDB(B1, 0, 1); PG8_SCHED; PG8_LDA(At, 0, 0); PG8_STAGE(PG8_SA(1, 1), a1 + hstep, voffA);
;             PG8_WAIT_V(8); PG8_WAIT_L(0); PG8_BAR; PG8_MMA(0, 0, At, B0); PG8_MMA(0, 1, At, B1); PG8_BAR; PG8_SCHED;
;             PG8_LDA(At, 0, 1); PG8_STAGE(PG8_SB(0, 0), b2, voffB); PG8_STAGE(PG8_SB(0, 1), b2 + hstep, voffB); PG8_STAGE(PG8_SA(0, 0), a2, voffA);
;             PG8_WAIT_V(8); PG8_WAIT_L(0); PG8_BAR; PG8_MMA(1, 0, At, B0); PG8_MMA(1, 1, At, B1); PG8_BAR; PG8_SCHED;
.LBB0_248:
	v_add_u32_e32 v155, s68, v149
	ds_read_b128 v[166:169], v155
	ds_read_b128 v[170:173], v155 offset:1024
	ds_read_b128 v[174:177], v155 offset:2048
	ds_read_b128 v[178:181], v155 offset:3072
	v_add_u32_e32 v155, s69, v149
	ds_read_b128 v[182:185], v155
	ds_read_b128 v[186:189], v155 offset:1024
	ds_read_b128 v[190:193], v155 offset:2048
	ds_read_b128 v[194:197], v155 offset:3072
	s_add_u32 s33, s50, 0xfffc0080
	s_addc_u32 s54, s51, -1
	s_and_b64 s[52:53], s[52:53], exec
	s_cselect_b32 s55, s25, s54
	s_cselect_b32 s54, s34, s33
	s_cselect_b32 s53, s21, s73
	s_cselect_b32 s52, s35, s72
	v_lshl_add_u64 v[210:211], s[50:51], 0, v[138:139]
	s_add_i32 m0, s59, 0xc000
	ds_read_b128 v[198:201], v153
	ds_read_b128 v[202:205], v153 offset:1024
	ds_read_b128 v[206:209], v153 offset:2048
	ds_read_b128 v[214:217], v153 offset:3072
	ds_read_b128 v[218:221], v153 offset:4096
	ds_read_b128 v[222:225], v153 offset:5120
	ds_read_b128 v[226:229], v153 offset:6144
	ds_read_b128 v[230:233], v153 offset:7168
	global_load_lds_dwordx4 v[210:211], off
	v_lshl_add_u64 v[210:211], s[50:51], 0, v[140:141]
	s_add_i32 m0, s59, 0xe000
	s_nop 0
	global_load_lds_dwordx4 v[210:211], off
	s_waitcnt vmcnt(8)
	s_waitcnt lgkmcnt(0)
	s_barrier
	s_waitcnt lgkmcnt(0)
	v_mfma_i32_16x16x64_i8 v[124:127], v[166:169], v[198:201], v[124:127]
	v_mfma_i32_16x16x64_i8 v[124:127], v[170:173], v[202:205], v[124:127]
	v_mfma_i32_16x16x64_i8 v[116:119], v[174:177], v[198:201], v[116:119]
	v_mfma_i32_16x16x64_i8 v[116:119], v[178:181], v[202:205], v[116:119]
	v_mfma_i32_16x16x64_i8 v[108:111], v[166:169], v[206:209], v[108:111]
	v_mfma_i32_16x16x64_i8 v[108:111], v[170:173], v[214:217], v[108:111]
	v_mfma_i32_16x16x64_i8 v[100:103], v[174:177], v[206:209], v[100:103]
	v_mfma_i32_16x16x64_i8 v[100:103], v[178:181], v[214:217], v[100:103]
	v_mfma_i32_16x16x64_i8 v[92:95], v[166:169], v[218:221], v[92:95]
	v_mfma_i32_16x16x64_i8 v[92:95], v[170:173], v[222:225], v[92:95]
	v_mfma_i32_16x16x64_i8 v[84:87], v[174:177], v[218:221], v[84:87]
	v_mfma_i32_16x16x64_i8 v[84:87], v[178:181], v[222:225], v[84:87]
	v_mfma_i32_16x16x64_i8 v[76:79], v[166:169], v[226:229], v[76:79]
	v_mfma_i32_16x16x64_i8 v[76:79], v[170:173], v[230:233], v[76:79]
	v_mfma_i32_16x16x64_i8 v[68:71], v[174:177], v[226:229], v[68:71]
	v_mfma_i32_16x16x64_i8 v[68:71], v[178:181], v[230:233], v[68:71]
	v_mfma_i32_16x16x64_i8 v[120:123], v[182:185], v[198:201], v[120:123]
	v_mfma_i32_16x16x64_i8 v[120:123], v[186:189], v[202:205], v[120:123]
	v_mfma_i32_16x16x64_i8 v[112:115], v[190:193], v[198:201], v[112:115]
	v_mfma_i32_16x16x64_i8 v[112:115], v[194:197], v[202:205], v[112:115]
	v_mfma_i32_16x16x64_i8 v[104:107], v[182:185], v[206:209], v[104:107]
	v_mfma_i32_16x16x64_i8 v[104:107], v[186:189], v[214:217], v[104:107]
	v_mfma_i32_16x16x64_i8 v[96:99], v[190:193], v[206:209], v[96:99]
	v_mfma_i32_16x16x64_i8 v[96:99], v[194:197], v[214:217], v[96:99]
	v_mfma_i32_16x16x64_i8 v[88:91], v[182:185], v[218:221], v[88:91]
	v_mfma_i32_16x16x64_i8 v[88:91], v[186:189], v[222:225], v[88:91]
	v_mfma_i32_16x16x64_i8 v[80:83], v[190:193], v[218:221], v[80:83]
	v_mfma_i32_16x16x64_i8 v[80:83], v[194:197], v[222:225], v[80:83]
	v_mfma_i32_16x16x64_i8 v[72:75], v[182:185], v[226:229], v[72:75]
	v_mfma_i32_16x16x64_i8 v[72:75], v[186:189], v[230:233], v[72:75]
	v_mfma_i32_16x16x64_i8 v[64:67], v[190:193], v[226:229], v[64:67]
	v_mfma_i32_16x16x64_i8 v[64:67], v[194:197], v[230:233], v[64:67]
	s_barrier
	s_add_i32 s33, s68, s56
	v_lshl_add_u64 v[210:211], s[52:53], 0, v[132:133]
	s_mov_b32 m0, s33
	ds_read_b128 v[198:201], v153 offset:16384
	ds_read_b128 v[202:205], v153 offset:17408
	ds_read_b128 v[206:209], v153 offset:18432
	ds_read_b128 v[214:217], v153 offset:19456
	ds_read_b128 v[218:221], v153 offset:20480
	ds_read_b128 v[222:225], v153 offset:21504
	ds_read_b128 v[226:229], v153 offset:22528
	ds_read_b128 v[230:233], v153 offset:23552
	global_load_lds_dwordx4 v[210:211], off
	s_add_i32 m0, s33, 0x2000
	s_add_u32 s76, s52, 0x40000
	v_lshl_add_u64 v[234:235], s[52:53], 0, v[128:129]
	s_addc_u32 s77, s53, 0
	s_add_i32 s33, s69, s56
	global_load_lds_dwordx4 v[234:235], off
	v_lshl_add_u64 v[236:237], s[76:77], 0, v[132:133]
	s_mov_b32 m0, s33
	v_lshl_add_u64 v[238:239], s[54:55], 0, v[130:131]
	global_load_lds_dwordx4 v[236:237], off
	v_lshl_add_u64 v[236:237], s[76:77], 0, v[128:129]
	s_add_i32 m0, s33, 0x2000
	s_nop 0
	global_load_lds_dwordx4 v[236:237], off
	v_lshl_add_u64 v[236:237], s[54:55], 0, v[134:135]
	s_mov_b32 m0, s59
	s_nop 0
	global_load_lds_dwordx4 v[236:237], off
	s_mov_b32 m0, s60
	s_nop 0
	global_load_lds_dwordx4 v[238:239], off
	s_waitcnt vmcnt(8)
	s_waitcnt lgkmcnt(0)
	s_barrier
; #define PG8_STAGE(bufoff, gbase, voff) do { _Pragma("unroll") for (int _i = 0; _i < 2; ++_i) \
;         __builtin_amdgcn_global_load_lds((const unsigned*)((const char*)(gbase) + (voff)[_i]), (PG8_LAS unsigned*)(lds + (bufoff) + ldsw + _i * 8192), 16, 0, 0); } while (0)
; #define PG8_WAIT_V(n) asm volatile("s_waitcnt vmcnt(" #n ")" ::: "memory")
; #define PG8_WAIT_L(n) asm volatile("s_waitcnt lgkmcnt(" #n ")" ::: "memory")
; #define PG8_BAR __builtin_amdgcn_s_barrier()
; #define PG8_SCHED __builtin_amdgcn_sched_barrier(0)
;     ...
;             PG8_WAIT_V(8); PG8_WAIT_L(0); PG8_BAR; PG8_MMA(1, 0, At, B0); PG8_MMA(1, 1, At, B1); PG8_BAR; PG8_SCHED;
;             PG8_LDB(B0, 1, 0); PG8_LDB(B1, 1, 1); PG8_SCHED; PG8_LDA(At, 1, 0); PG8_STAGE(PG8_SA(0, 1), a2 + hstep, voffA);
;             PG8_WAIT_V(8); PG8_WAIT_L(0); PG8_BAR; PG8_MMA(0, 0, At, B0); PG8_MMA(0, 1, At, B1); PG8_BAR; PG8_SCHED;
	s_waitcnt lgkmcnt(0)
	v_mfma_i32_16x16x64_i8 v[60:63], v[166:169], v[198:201], v[60:63]
	v_mfma_i32_16x16x64_i8 v[60:63], v[170:173], v[202:205], v[60:63]
	v_mfma_i32_16x16x64_i8 v[52:55], v[174:177], v[198:201], v[52:55]
	v_mfma_i32_16x16x64_i8 v[52:55], v[178:181], v[202:205], v[52:55]
	v_mfma_i32_16x16x64_i8 v[44:47], v[166:169], v[206:209], v[44:47]
	v_mfma_i32_16x16x64_i8 v[44:47], v[170:173], v[214:217], v[44:47]
	v_mfma_i32_16x16x64_i8 v[36:39], v[174:177], v[206:209], v[36:39]
	v_mfma_i32_16x16x64_i8 v[36:39], v[178:181], v[214:217], v[36:39]
	v_mfma_i32_16x16x64_i8 v[28:31], v[166:169], v[218:221], v[28:31]
	v_mfma_i32_16x16x64_i8 v[28:31], v[170:173], v[222:225], v[28:31]
	v_mfma_i32_16x16x64_i8 v[20:23], v[174:177], v[218:221], v[20:23]
	v_mfma_i32_16x16x64_i8 v[20:23], v[178:181], v[222:225], v[20:23]
	v_mfma_i32_16x16x64_i8 v[12:15], v[166:169], v[226:229], v[12:15]
	v_mfma_i32_16x16x64_i8 v[12:15], v[170:173], v[230:233], v[12:15]
	v_mfma_i32_16x16x64_i8 v[4:7], v[174:177], v[226:229], v[4:7]
	v_mfma_i32_16x16x64_i8 v[4:7], v[178:181], v[230:233], v[4:7]
	v_mfma_i32_16x16x64_i8 v[56:59], v[182:185], v[198:201], v[56:59]
	v_mfma_i32_16x16x64_i8 v[56:59], v[186:189], v[202:205], v[56:59]
	v_mfma_i32_16x16x64_i8 v[48:51], v[190:193], v[198:201], v[48:51]
	v_mfma_i32_16x16x64_i8 v[48:51], v[194:197], v[202:205], v[48:51]
	v_mfma_i32_16x16x64_i8 v[40:43], v[182:185], v[206:209], v[40:43]
	v_mfma_i32_16x16x64_i8 v[40:43], v[186:189], v[214:217], v[40:43]
	v_mfma_i32_16x16x64_i8 v[32:35], v[190:193], v[206:209], v[32:35]
	v_mfma_i32_16x16x64_i8 v[32:35], v[194:197], v[214:217], v[32:35]
	v_mfma_i32_16x16x64_i8 v[24:27], v[182:185], v[218:221], v[24:27]
	v_mfma_i32_16x16x64_i8 v[24:27], v[186:189], v[222:225], v[24:27]
	v_mfma_i32_16x16x64_i8 v[16:19], v[190:193], v[218:221], v[16:19]
	v_mfma_i32_16x16x64_i8 v[16:19], v[194:197], v[222:225], v[16:19]
	v_mfma_i32_16x16x64_i8 v[8:11], v[182:185], v[226:229], v[8:11]
	v_mfma_i32_16x16x64_i8 v[8:11], v[186:189], v[230:233], v[8:11]
	v_mfma_i32_16x16x64_i8 v[0:3], v[190:193], v[226:229], v[0:3]
	v_mfma_i32_16x16x64_i8 v[0:3], v[194:197], v[230:233], v[0:3]
	s_barrier
	s_add_i32 s33, 0, 0x18000
	v_add_u32_e32 v155, s33, v149
	s_add_i32 s75, 0, 0x1c000
	ds_read_b128 v[166:169], v155
	ds_read_b128 v[170:173], v155 offset:1024
	ds_read_b128 v[174:177], v155 offset:2048
	ds_read_b128 v[178:181], v155 offset:3072
	v_add_u32_e32 v155, s75, v149
	ds_read_b128 v[182:185], v155
	ds_read_b128 v[186:189], v155 offset:1024
	ds_read_b128 v[190:193], v155 offset:2048
	ds_read_b128 v[194:197], v155 offset:3072
	s_add_u32 s54, s54, 0x40000
	s_addc_u32 s55, s55, 0
	s_mov_b32 m0, s61
	v_lshl_add_u64 v[240:241], s[54:55], 0, v[134:135]
	ds_read_b128 v[198:201], v153 offset:32768
	ds_read_b128 v[202:205], v153 offset:33792
	ds_read_b128 v[206:209], v153 offset:34816
	ds_read_b128 v[214:217], v153 offset:35840
	ds_read_b128 v[218:221], v153 offset:36864
	ds_read_b128 v[222:225], v153 offset:37888
	ds_read_b128 v[226:229], v153 offset:38912
	ds_read_b128 v[230:233], v153 offset:39936
	global_load_lds_dwordx4 v[240:241], off
	v_lshl_add_u64 v[240:241], s[54:55], 0, v[130:131]
	s_mov_b32 m0, s62
	s_nop 0
	global_load_lds_dwordx4 v[240:241], off
	s_waitcnt vmcnt(8)
	s_waitcnt lgkmcnt(0)
	s_barrier
	s_waitcnt lgkmcnt(0)
	v_mfma_i32_16x16x64_i8 v[124:127], v[166:169], v[198:201], v[124:127]
	v_mfma_i32_16x16x64_i8 v[124:127], v[170:173], v[202:205], v[124:127]
	v_mfma_i32_16x16x64_i8 v[116:119], v[174:177], v[198:201], v[116:119]
	v_mfma_i32_16x16x64_i8 v[116:119], v[178:181], v[202:205], v[116:119]
	v_mfma_i32_16x16x64_i8 v[108:111], v[166:169], v[206:209], v[108:111]
	v_mfma_i32_16x16x64_i8 v[108:111], v[170:173], v[214:217], v[108:111]
	v_mfma_i32_16x16x64_i8 v[100:103], v[174:177], v[206:209], v[100:103]
	v_mfma_i32_16x16x64_i8 v[100:103], v[178:181], v[214:217], v[100:103]
	v_mfma_i32_16x16x64_i8 v[92:95], v[166:169], v[218:221], v[92:95]
	v_mfma_i32_16x16x64_i8 v[92:95], v[170:173], v[222:225], v[92:95]
	v_mfma_i32_16x16x64_i8 v[84:87], v[174:177], v[218:221], v[84:87]
	v_mfma_i32_16x16x64_i8 v[84:87], v[178:181], v[222:225], v[84:87]
	v_mfma_i32_16x16x64_i8 v[76:79], v[166:169], v[226:229], v[76:79]
	v_mfma_i32_16x16x64_i8 v[76:79], v[170:173], v[230:233], v[76:79]
	v_mfma_i32_16x16x64_i8 v[68:71], v[174:177], v[226:229], v[68:71]
	v_mfma_i32_16x16x64_i8 v[68:71], v[178:181], v[230:233], v[68:71]
	v_mfma_i32_16x16x64_i8 v[120:123], v[182:185], v[198:201], v[120:123]
	v_mfma_i32_16x16x64_i8 v[120:123], v[186:189], v[202:205], v[120:123]
	v_mfma_i32_16x16x64_i8 v[112:115], v[190:193], v[198:201], v[112:115]
	v_mfma_i32_16x16x64_i8 v[112:115], v[194:197], v[202:205], v[112:115]
	v_mfma_i32_16x16x64_i8 v[104:107], v[182:185], v[206:209], v[104:107]
	v_mfma_i32_16x16x64_i8 v[104:107], v[186:189], v[214:217], v[104:107]
	v_mfma_i32_16x16x64_i8 v[96:99], v[190:193], v[206:209], v[96:99]
	v_mfma_i32_16x16x64_i8 v[96:99], v[194:197], v[214:217], v[96:99]
	v_mfma_i32_16x16x64_i8 v[88:91], v[182:185], v[218:221], v[88:91]
	v_mfma_i32_16x16x64_i8 v[88:91], v[186:189], v[222:225], v[88:91]
	v_mfma_i32_16x16x64_i8 v[80:83], v[190:193], v[218:221], v[80:83]
	v_mfma_i32_16x16x64_i8 v[80:83], v[194:197], v[222:225], v[80:83]
	v_mfma_i32_16x16x64_i8 v[72:75], v[182:185], v[226:229], v[72:75]
	v_mfma_i32_16x16x64_i8 v[72:75], v[186:189], v[230:233], v[72:75]
	v_mfma_i32_16x16x64_i8 v[64:67], v[190:193], v[226:229], v[64:67]
	v_mfma_i32_16x16x64_i8 v[64:67], v[194:197], v[230:233], v[64:67]
	s_barrier
; #define PG8_STAGE(bufoff, gbase, voff) do { _Pragma("unroll") for (int _i = 0; _i < 2; ++_i) \
;         __builtin_amdgcn_global_load_lds((const unsigned*)((const char*)(gbase) + (voff)[_i]), (PG8_LAS unsigned*)(lds + (bufoff) + ldsw + _i * 8192), 16, 0, 0); } while (0)
; #define PG8_WAIT_V(n) asm volatile("s_waitcnt vmcnt(" #n ")" ::: "memory")
; #define PG8_WAIT_L(n) asm volatile("s_waitcnt lgkmcnt(" #n ")" ::: "memory")
; #define PG8_BAR __builtin_amdgcn_s_barrier()
; #define PG8_SCHED __builtin_amdgcn_sched_barrier(0)
;     ...
;             PG8_LDA(At, 1, 1); PG8_STAGE(PG8_SB(1, 0), b3, voffB); PG8_STAGE(PG8_SB(1, 1), b3 + hstep, voffB); PG8_STAGE(PG8_SA(1, 0), a3, voffA);
;             PG8_WAIT_V(8); PG8_WAIT_L(0); PG8_BAR; PG8_MMA(1, 0, At, B0); PG8_MMA(1, 1, At, B1); PG8_BAR; PG8_SCHED;
	s_add_i32 s33, s33, s56
	v_lshl_add_u64 v[210:211], v[210:211], 0, s[10:11]
	s_mov_b32 m0, s33
	ds_read_b128 v[198:201], v153 offset:49152
	ds_read_b128 v[202:205], v153 offset:50176
	ds_read_b128 v[206:209], v153 offset:51200
	ds_read_b128 v[214:217], v153 offset:52224
	ds_read_b128 v[218:221], v153 offset:53248
	ds_read_b128 v[222:225], v153 offset:54272
	ds_read_b128 v[226:229], v153 offset:55296
	ds_read_b128 v[230:233], v153 offset:56320
	global_load_lds_dwordx4 v[210:211], off
	s_add_i32 m0, s33, 0x2000
	s_add_u32 s52, s52, 0x40080
	v_lshl_add_u64 v[210:211], v[234:235], 0, s[10:11]
	s_addc_u32 s53, s53, 0
	s_add_i32 s33, s75, s56
	global_load_lds_dwordx4 v[210:211], off
	v_lshl_add_u64 v[210:211], s[52:53], 0, v[132:133]
	s_mov_b32 m0, s33
	s_nop 0
	global_load_lds_dwordx4 v[210:211], off
	v_lshl_add_u64 v[210:211], s[52:53], 0, v[128:129]
	s_add_i32 m0, s33, 0x2000
	s_nop 0
	global_load_lds_dwordx4 v[210:211], off
	v_lshl_add_u64 v[210:211], v[236:237], 0, s[10:11]
	s_mov_b32 m0, s64
	s_nop 0
	global_load_lds_dwordx4 v[210:211], off
	v_lshl_add_u64 v[210:211], v[238:239], 0, s[10:11]
	s_mov_b32 m0, s65
	s_nop 0
	global_load_lds_dwordx4 v[210:211], off
	s_waitcnt vmcnt(8)
	s_waitcnt lgkmcnt(0)
	s_barrier
	s_waitcnt lgkmcnt(0)
	v_mfma_i32_16x16x64_i8 v[60:63], v[166:169], v[198:201], v[60:63]
	v_mfma_i32_16x16x64_i8 v[60:63], v[170:173], v[202:205], v[60:63]
	v_mfma_i32_16x16x64_i8 v[52:55], v[174:177], v[198:201], v[52:55]
	v_mfma_i32_16x16x64_i8 v[52:55], v[178:181], v[202:205], v[52:55]
	v_mfma_i32_16x16x64_i8 v[44:47], v[166:169], v[206:209], v[44:47]
	v_mfma_i32_16x16x64_i8 v[44:47], v[170:173], v[214:217], v[44:47]
	v_mfma_i32_16x16x64_i8 v[36:39], v[174:177], v[206:209], v[36:39]
	v_mfma_i32_16x16x64_i8 v[36:39], v[178:181], v[214:217], v[36:39]
	v_mfma_i32_16x16x64_i8 v[28:31], v[166:169], v[218:221], v[28:31]
	v_mfma_i32_16x16x64_i8 v[28:31], v[170:173], v[222:225], v[28:31]
	v_mfma_i32_16x16x64_i8 v[20:23], v[174:177], v[218:221], v[20:23]
	v_mfma_i32_16x16x64_i8 v[20:23], v[178:181], v[222:225], v[20:23]
	v_mfma_i32_16x16x64_i8 v[12:15], v[166:169], v[226:229], v[12:15]
	v_mfma_i32_16x16x64_i8 v[12:15], v[170:173], v[230:233], v[12:15]
	v_mfma_i32_16x16x64_i8 v[4:7], v[174:177], v[226:229], v[4:7]
	v_mfma_i32_16x16x64_i8 v[4:7], v[178:181], v[230:233], v[4:7]
	v_mfma_i32_16x16x64_i8 v[56:59], v[182:185], v[198:201], v[56:59]
	v_mfma_i32_16x16x64_i8 v[56:59], v[186:189], v[202:205], v[56:59]
	v_mfma_i32_16x16x64_i8 v[48:51], v[190:193], v[198:201], v[48:51]
	v_mfma_i32_16x16x64_i8 v[48:51], v[194:197], v[202:205], v[48:51]
	v_mfma_i32_16x16x64_i8 v[40:43], v[182:185], v[206:209], v[40:43]
	v_mfma_i32_16x16x64_i8 v[40:43], v[186:189], v[214:217], v[40:43]
	v_mfma_i32_16x16x64_i8 v[32:35], v[190:193], v[206:209], v[32:35]
	v_mfma_i32_16x16x64_i8 v[32:35], v[194:197], v[214:217], v[32:35]
	v_mfma_i32_16x16x64_i8 v[24:27], v[182:185], v[218:221], v[24:27]
	v_mfma_i32_16x16x64_i8 v[24:27], v[186:189], v[222:225], v[24:27]
	v_mfma_i32_16x16x64_i8 v[16:19], v[190:193], v[218:221], v[16:19]
	v_mfma_i32_16x16x64_i8 v[16:19], v[194:197], v[222:225], v[16:19]
	v_mfma_i32_16x16x64_i8 v[8:11], v[182:185], v[226:229], v[8:11]
	v_mfma_i32_16x16x64_i8 v[8:11], v[186:189], v[230:233], v[8:11]
	v_mfma_i32_16x16x64_i8 v[0:3], v[190:193], v[226:229], v[0:3]
	v_mfma_i32_16x16x64_i8 v[0:3], v[194:197], v[230:233], v[0:3]
	s_barrier
	s_add_i32 s74, s74, 2
	s_add_u32 s50, s50, 0x100
	s_addc_u32 s51, s51, 0
	s_add_u32 s72, s72, 0x100
	s_addc_u32 s73, s73, 0
	s_cmp_gt_u32 s74, 13
	s_cbranch_scc1 .LBB0_251

; #define PG8_STAGE(bufoff, gbase, voff) do { _Pragma("unroll") for (int _i = 0; _i < 2; ++_i) \
;         __builtin_amdgcn_global_load_lds((const unsigned*)((const char*)(gbase) + (voff)[_i]), (PG8_LAS unsigned*)(lds + (bufoff) + ldsw + _i * 8192), 16, 0, 0); } while (0)
; #define PG8_WAIT_V(n) asm volatile("s_waitcnt vmcnt(" #n ")" ::: "memory")
; #define PG8_WAIT_L(n) asm volatile("s_waitcnt lgkmcnt(" #n ")" ::: "memory")
; #define PG8_BAR __builtin_amdgcn_s_barrier()
; #define PG8_SCHED __builtin_amdgcn_sched_barrier(0)
;     ...
;             const char* a1 = cA + (size_t)(t + 1) * kstep;
;             const char* a2 = last ? nA : cA + (size_t)(t + 2) * kstep; const char* b2 = last ? nB : cB + (size_t)(t + 2) * kstep;
;             const char* a3 = a2 + kstep; const char* b3 = b2 + kstep;
;             if (last && has_next) S.a_ready(nxt);
;             if (last) E.pre(pre, cur, wr, fr);
;             if constexpr (MIDK > 0) { if (t == MIDK / BK) E.mid(acc, cur, wr, wc, fr, fq); }
;             if constexpr (SP2) {
;             PG8_LDB(B0, 0, 0); PG8_LDB(B1, 0, 1); PG8_SCHED; PG8_LDA(At, 0, 0); PG8_STAGE(PG8_SA(1, 1), a1 + hstep, voffA);
;             PG8_WAIT_V(8); PG8_WAIT_L(0); PG8_BAR; PG8_MMA(0, 0, At, B0); PG8_MMA(0, 1, At, B1); PG8_BAR; PG8_SCHED;
;             PG8_LDA(At, 0, 1); PG8_STAGE(PG8_SB(0, 0), b2, voffB); PG8_STAGE(PG8_SB(0, 1), b2 + hstep, voffB); PG8_STAGE(PG8_SA(0, 0), a2, voffA);
;             PG8_WAIT_V(8); PG8_WAIT_L(0); PG8_BAR; PG8_MMA(1, 0, At, B0); PG8_MMA(1, 1, At, B1); PG8_BAR; PG8_SCHED;
.LBB0_335:
	ds_read_b128 v[128:131], v191
	ds_read_b128 v[132:135], v191 offset:1024
	ds_read_b128 v[136:139], v191 offset:2048
	ds_read_b128 v[140:143], v191 offset:3072
	ds_read_b128 v[144:147], v192
	ds_read_b128 v[148:151], v192 offset:1024
	ds_read_b128 v[168:171], v192 offset:2048
	ds_read_b128 v[172:175], v192 offset:3072
	s_add_u32 s33, s50, 0xffea0080
	s_addc_u32 s52, s51, -1
	s_cmpk_eq_i32 s72, 0x54
	s_cselect_b32 s55, s1, s52
	s_cselect_b32 s54, s0, s33
	s_cselect_b32 s53, s49, s35
	s_cselect_b32 s52, s48, s34
	v_lshl_add_u64 v[218:219], s[50:51], 0, v[160:161]
	s_add_i32 m0, s56, 0xc000
	ds_read_b128 v[176:179], v193
	ds_read_b128 v[180:183], v193 offset:1024
	ds_read_b128 v[184:187], v193 offset:2048
	ds_read_b128 v[196:199], v193 offset:3072
	ds_read_b128 v[200:203], v193 offset:4096
	ds_read_b128 v[204:207], v193 offset:5120
	ds_read_b128 v[208:211], v193 offset:6144
	ds_read_b128 v[214:217], v193 offset:7168
	global_load_lds_dwordx4 v[218:219], off
	v_lshl_add_u64 v[218:219], s[50:51], 0, v[162:163]
	s_add_i32 m0, s56, 0xe000
	s_nop 0
	global_load_lds_dwordx4 v[218:219], off
	s_waitcnt vmcnt(8)
	s_waitcnt lgkmcnt(0)
	s_barrier
	s_waitcnt lgkmcnt(0)
	v_mfma_f32_16x16x32_bf16 v[124:127], v[128:131], v[176:179], v[124:127]
	v_mfma_f32_16x16x32_bf16 v[124:127], v[132:135], v[180:183], v[124:127]
	v_mfma_f32_16x16x32_bf16 v[120:123], v[136:139], v[176:179], v[120:123]
	v_mfma_f32_16x16x32_bf16 v[120:123], v[140:143], v[180:183], v[120:123]
	v_mfma_f32_16x16x32_bf16 v[108:111], v[128:131], v[184:187], v[108:111]
	v_mfma_f32_16x16x32_bf16 v[108:111], v[132:135], v[196:199], v[108:111]
	v_mfma_f32_16x16x32_bf16 v[104:107], v[136:139], v[184:187], v[104:107]
	v_mfma_f32_16x16x32_bf16 v[104:107], v[140:143], v[196:199], v[104:107]
	v_mfma_f32_16x16x32_bf16 v[92:95], v[128:131], v[200:203], v[92:95]
	v_mfma_f32_16x16x32_bf16 v[92:95], v[132:135], v[204:207], v[92:95]
	v_mfma_f32_16x16x32_bf16 v[88:91], v[136:139], v[200:203], v[88:91]
	v_mfma_f32_16x16x32_bf16 v[88:91], v[140:143], v[204:207], v[88:91]
	v_mfma_f32_16x16x32_bf16 v[76:79], v[128:131], v[208:211], v[76:79]
	v_mfma_f32_16x16x32_bf16 v[76:79], v[132:135], v[214:217], v[76:79]
	v_mfma_f32_16x16x32_bf16 v[72:75], v[136:139], v[208:211], v[72:75]
	v_mfma_f32_16x16x32_bf16 v[72:75], v[140:143], v[214:217], v[72:75]
	v_mfma_f32_16x16x32_bf16 v[116:119], v[144:147], v[176:179], v[116:119]
	v_mfma_f32_16x16x32_bf16 v[116:119], v[148:151], v[180:183], v[116:119]
	v_mfma_f32_16x16x32_bf16 v[112:115], v[168:171], v[176:179], v[112:115]
	v_mfma_f32_16x16x32_bf16 v[112:115], v[172:175], v[180:183], v[112:115]
	v_mfma_f32_16x16x32_bf16 v[100:103], v[144:147], v[184:187], v[100:103]
	v_mfma_f32_16x16x32_bf16 v[100:103], v[148:151], v[196:199], v[100:103]
	v_mfma_f32_16x16x32_bf16 v[96:99], v[168:171], v[184:187], v[96:99]
	v_mfma_f32_16x16x32_bf16 v[96:99], v[172:175], v[196:199], v[96:99]
	v_mfma_f32_16x16x32_bf16 v[84:87], v[144:147], v[200:203], v[84:87]
	v_mfma_f32_16x16x32_bf16 v[84:87], v[148:151], v[204:207], v[84:87]
	v_mfma_f32_16x16x32_bf16 v[80:83], v[168:171], v[200:203], v[80:83]
	v_mfma_f32_16x16x32_bf16 v[80:83], v[172:175], v[204:207], v[80:83]
	v_mfma_f32_16x16x32_bf16 v[68:71], v[144:147], v[208:211], v[68:71]
	v_mfma_f32_16x16x32_bf16 v[68:71], v[148:151], v[214:217], v[68:71]
	v_mfma_f32_16x16x32_bf16 v[64:67], v[168:171], v[208:211], v[64:67]
	v_mfma_f32_16x16x32_bf16 v[64:67], v[172:175], v[214:217], v[64:67]
	s_barrier
	s_add_i32 s33, s66, s19
	v_lshl_add_u64 v[218:219], s[52:53], 0, v[154:155]
	s_mov_b32 m0, s33
	ds_read_b128 v[176:179], v193 offset:16384
	ds_read_b128 v[180:183], v193 offset:17408
	ds_read_b128 v[184:187], v193 offset:18432
	ds_read_b128 v[196:199], v193 offset:19456
	ds_read_b128 v[200:203], v193 offset:20480
	ds_read_b128 v[204:207], v193 offset:21504
	ds_read_b128 v[208:211], v193 offset:22528
	ds_read_b128 v[214:217], v193 offset:23552
	global_load_lds_dwordx4 v[218:219], off
	s_add_i32 m0, s33, 0x2000
	s_add_u32 s74, s52, 0x160000
	v_lshl_add_u64 v[220:221], s[52:53], 0, v[158:159]
	s_addc_u32 s75, s53, 0
	s_add_i32 s33, s67, s19
	global_load_lds_dwordx4 v[220:221], off
	v_lshl_add_u64 v[222:223], s[74:75], 0, v[154:155]
	s_mov_b32 m0, s33
	v_lshl_add_u64 v[224:225], s[54:55], 0, v[156:157]
	global_load_lds_dwordx4 v[222:223], off
	v_lshl_add_u64 v[222:223], s[74:75], 0, v[158:159]
	s_add_i32 m0, s33, 0x2000
	s_nop 0
	global_load_lds_dwordx4 v[222:223], off
	v_lshl_add_u64 v[222:223], s[54:55], 0, v[152:153]
	s_mov_b32 m0, s56
	s_nop 0
	global_load_lds_dwordx4 v[222:223], off
	s_mov_b32 m0, s57
	s_nop 0
	global_load_lds_dwordx4 v[224:225], off
	s_waitcnt vmcnt(8)
	s_waitcnt lgkmcnt(0)
	s_barrier
; #define PG8_STAGE(bufoff, gbase, voff) do { _Pragma("unroll") for (int _i = 0; _i < 2; ++_i) \
;         __builtin_amdgcn_global_load_lds((const unsigned*)((const char*)(gbase) + (voff)[_i]), (PG8_LAS unsigned*)(lds + (bufoff) + ldsw + _i * 8192), 16, 0, 0); } while (0)
; #define PG8_WAIT_V(n) asm volatile("s_waitcnt vmcnt(" #n ")" ::: "memory")
; #define PG8_WAIT_L(n) asm volatile("s_waitcnt lgkmcnt(" #n ")" ::: "memory")
; #define PG8_BAR __builtin_amdgcn_s_barrier()
; #define PG8_SCHED __builtin_amdgcn_sched_barrier(0)
;     ...
;             PG8_WAIT_V(8); PG8_WAIT_L(0); PG8_BAR; PG8_MMA(1, 0, At, B0); PG8_MMA(1, 1, At, B1); PG8_BAR; PG8_SCHED;
;             PG8_LDB(B0, 1, 0); PG8_LDB(B1, 1, 1); PG8_SCHED; PG8_LDA(At, 1, 0); PG8_STAGE(PG8_SA(0, 1), a2 + hstep, voffA);
;             PG8_WAIT_V(8); PG8_WAIT_L(0); PG8_BAR; PG8_MMA(0, 0, At, B0); PG8_MMA(0, 1, At, B1); PG8_BAR; PG8_SCHED;
	s_waitcnt lgkmcnt(0)
	v_mfma_f32_16x16x32_bf16 v[60:63], v[128:131], v[176:179], v[60:63]
	v_mfma_f32_16x16x32_bf16 v[60:63], v[132:135], v[180:183], v[60:63]
	v_mfma_f32_16x16x32_bf16 v[56:59], v[136:139], v[176:179], v[56:59]
	v_mfma_f32_16x16x32_bf16 v[56:59], v[140:143], v[180:183], v[56:59]
	v_mfma_f32_16x16x32_bf16 v[44:47], v[128:131], v[184:187], v[44:47]
	v_mfma_f32_16x16x32_bf16 v[44:47], v[132:135], v[196:199], v[44:47]
	v_mfma_f32_16x16x32_bf16 v[40:43], v[136:139], v[184:187], v[40:43]
	v_mfma_f32_16x16x32_bf16 v[40:43], v[140:143], v[196:199], v[40:43]
	v_mfma_f32_16x16x32_bf16 v[28:31], v[128:131], v[200:203], v[28:31]
	v_mfma_f32_16x16x32_bf16 v[28:31], v[132:135], v[204:207], v[28:31]
	v_mfma_f32_16x16x32_bf16 v[24:27], v[136:139], v[200:203], v[24:27]
	v_mfma_f32_16x16x32_bf16 v[24:27], v[140:143], v[204:207], v[24:27]
	v_mfma_f32_16x16x32_bf16 v[12:15], v[128:131], v[208:211], v[12:15]
	v_mfma_f32_16x16x32_bf16 v[12:15], v[132:135], v[214:217], v[12:15]
	v_mfma_f32_16x16x32_bf16 v[8:11], v[136:139], v[208:211], v[8:11]
	v_mfma_f32_16x16x32_bf16 v[8:11], v[140:143], v[214:217], v[8:11]
	v_mfma_f32_16x16x32_bf16 v[52:55], v[144:147], v[176:179], v[52:55]
	v_mfma_f32_16x16x32_bf16 v[52:55], v[148:151], v[180:183], v[52:55]
	v_mfma_f32_16x16x32_bf16 v[48:51], v[168:171], v[176:179], v[48:51]
	v_mfma_f32_16x16x32_bf16 v[48:51], v[172:175], v[180:183], v[48:51]
	v_mfma_f32_16x16x32_bf16 v[36:39], v[144:147], v[184:187], v[36:39]
	v_mfma_f32_16x16x32_bf16 v[36:39], v[148:151], v[196:199], v[36:39]
	v_mfma_f32_16x16x32_bf16 v[32:35], v[168:171], v[184:187], v[32:35]
	v_mfma_f32_16x16x32_bf16 v[32:35], v[172:175], v[196:199], v[32:35]
	v_mfma_f32_16x16x32_bf16 v[20:23], v[144:147], v[200:203], v[20:23]
	v_mfma_f32_16x16x32_bf16 v[20:23], v[148:151], v[204:207], v[20:23]
	v_mfma_f32_16x16x32_bf16 v[16:19], v[168:171], v[200:203], v[16:19]
	v_mfma_f32_16x16x32_bf16 v[16:19], v[172:175], v[204:207], v[16:19]
	v_mfma_f32_16x16x32_bf16 v[4:7], v[144:147], v[208:211], v[4:7]
	v_mfma_f32_16x16x32_bf16 v[4:7], v[148:151], v[214:217], v[4:7]
	v_mfma_f32_16x16x32_bf16 v[0:3], v[168:171], v[208:211], v[0:3]
	v_mfma_f32_16x16x32_bf16 v[0:3], v[172:175], v[214:217], v[0:3]
	s_barrier
	s_add_i32 s33, 0, 0x18000
	s_add_i32 s73, 0, 0x1c000
	v_add_u32_e32 v140, s33, v189
	v_add_u32_e32 v172, s73, v189
	ds_read_b128 v[128:131], v140
	ds_read_b128 v[132:135], v140 offset:1024
	ds_read_b128 v[136:139], v140 offset:2048
	ds_read_b128 v[140:143], v140 offset:3072
	ds_read_b128 v[144:147], v172
	ds_read_b128 v[148:151], v172 offset:1024
	ds_read_b128 v[168:171], v172 offset:2048
	ds_read_b128 v[172:175], v172 offset:3072
	s_add_u32 s54, s54, 0x160000
	s_addc_u32 s55, s55, 0
	s_mov_b32 m0, s58
	v_lshl_add_u64 v[226:227], s[54:55], 0, v[152:153]
	ds_read_b128 v[176:179], v193 offset:32768
	ds_read_b128 v[180:183], v193 offset:33792
	ds_read_b128 v[184:187], v193 offset:34816
	ds_read_b128 v[196:199], v193 offset:35840
	ds_read_b128 v[200:203], v193 offset:36864
	ds_read_b128 v[204:207], v193 offset:37888
	ds_read_b128 v[208:211], v193 offset:38912
	ds_read_b128 v[214:217], v193 offset:39936
	global_load_lds_dwordx4 v[226:227], off
	v_lshl_add_u64 v[226:227], s[54:55], 0, v[156:157]
	s_mov_b32 m0, s59
	s_nop 0
	global_load_lds_dwordx4 v[226:227], off
	s_waitcnt vmcnt(8)
	s_waitcnt lgkmcnt(0)
	s_barrier
	s_waitcnt lgkmcnt(0)
	v_mfma_f32_16x16x32_bf16 v[124:127], v[128:131], v[176:179], v[124:127]
	v_mfma_f32_16x16x32_bf16 v[124:127], v[132:135], v[180:183], v[124:127]
	v_mfma_f32_16x16x32_bf16 v[120:123], v[136:139], v[176:179], v[120:123]
	v_mfma_f32_16x16x32_bf16 v[120:123], v[140:143], v[180:183], v[120:123]
	v_mfma_f32_16x16x32_bf16 v[108:111], v[128:131], v[184:187], v[108:111]
	v_mfma_f32_16x16x32_bf16 v[108:111], v[132:135], v[196:199], v[108:111]
	v_mfma_f32_16x16x32_bf16 v[104:107], v[136:139], v[184:187], v[104:107]
	v_mfma_f32_16x16x32_bf16 v[104:107], v[140:143], v[196:199], v[104:107]
	v_mfma_f32_16x16x32_bf16 v[92:95], v[128:131], v[200:203], v[92:95]
	v_mfma_f32_16x16x32_bf16 v[92:95], v[132:135], v[204:207], v[92:95]
	v_mfma_f32_16x16x32_bf16 v[88:91], v[136:139], v[200:203], v[88:91]
	v_mfma_f32_16x16x32_bf16 v[88:91], v[140:143], v[204:207], v[88:91]
	v_mfma_f32_16x16x32_bf16 v[76:79], v[128:131], v[208:211], v[76:79]
	v_mfma_f32_16x16x32_bf16 v[76:79], v[132:135], v[214:217], v[76:79]
	v_mfma_f32_16x16x32_bf16 v[72:75], v[136:139], v[208:211], v[72:75]
	v_mfma_f32_16x16x32_bf16 v[72:75], v[140:143], v[214:217], v[72:75]
	v_mfma_f32_16x16x32_bf16 v[116:119], v[144:147], v[176:179], v[116:119]
	v_mfma_f32_16x16x32_bf16 v[116:119], v[148:151], v[180:183], v[116:119]
	v_mfma_f32_16x16x32_bf16 v[112:115], v[168:171], v[176:179], v[112:115]
	v_mfma_f32_16x16x32_bf16 v[112:115], v[172:175], v[180:183], v[112:115]
	v_mfma_f32_16x16x32_bf16 v[100:103], v[144:147], v[184:187], v[100:103]
	v_mfma_f32_16x16x32_bf16 v[100:103], v[148:151], v[196:199], v[100:103]
	v_mfma_f32_16x16x32_bf16 v[96:99], v[168:171], v[184:187], v[96:99]
	v_mfma_f32_16x16x32_bf16 v[96:99], v[172:175], v[196:199], v[96:99]
	v_mfma_f32_16x16x32_bf16 v[84:87], v[144:147], v[200:203], v[84:87]
	v_mfma_f32_16x16x32_bf16 v[84:87], v[148:151], v[204:207], v[84:87]
	v_mfma_f32_16x16x32_bf16 v[80:83], v[168:171], v[200:203], v[80:83]
	v_mfma_f32_16x16x32_bf16 v[80:83], v[172:175], v[204:207], v[80:83]
	v_mfma_f32_16x16x32_bf16 v[68:71], v[144:147], v[208:211], v[68:71]
	v_mfma_f32_16x16x32_bf16 v[68:71], v[148:151], v[214:217], v[68:71]
	v_mfma_f32_16x16x32_bf16 v[64:67], v[168:171], v[208:211], v[64:67]
	v_mfma_f32_16x16x32_bf16 v[64:67], v[172:175], v[214:217], v[64:67]
	s_barrier
; #define PG8_STAGE(bufoff, gbase, voff) do { _Pragma("unroll") for (int _i = 0; _i < 2; ++_i) \
;         __builtin_amdgcn_global_load_lds((const unsigned*)((const char*)(gbase) + (voff)[_i]), (PG8_LAS unsigned*)(lds + (bufoff) + ldsw + _i * 8192), 16, 0, 0); } while (0)
; #define PG8_WAIT_V(n) asm volatile("s_waitcnt vmcnt(" #n ")" ::: "memory")
; #define PG8_WAIT_L(n) asm volatile("s_waitcnt lgkmcnt(" #n ")" ::: "memory")
; #define PG8_BAR __builtin_amdgcn_s_barrier()
; #define PG8_SCHED __builtin_amdgcn_sched_barrier(0)
;     ...
;             PG8_LDA(At, 1, 1); PG8_STAGE(PG8_SB(1, 0), b3, voffB); PG8_STAGE(PG8_SB(1, 1), b3 + hstep, voffB); PG8_STAGE(PG8_SA(1, 0), a3, voffA);
;             PG8_WAIT_V(8); PG8_WAIT_L(0); PG8_BAR; PG8_MMA(1, 0, At, B0); PG8_MMA(1, 1, At, B1); PG8_BAR; PG8_SCHED;
;     ...
;         if constexpr (ALIGN_EPI) { if (wr == 0) PG8_BAR; }
	s_add_i32 s33, s33, s19
	v_lshl_add_u64 v[218:219], v[218:219], 0, s[24:25]
	s_mov_b32 m0, s33
	ds_read_b128 v[176:179], v193 offset:49152
	ds_read_b128 v[180:183], v193 offset:50176
	ds_read_b128 v[184:187], v193 offset:51200
	ds_read_b128 v[196:199], v193 offset:52224
	ds_read_b128 v[200:203], v193 offset:53248
	ds_read_b128 v[204:207], v193 offset:54272
	ds_read_b128 v[208:211], v193 offset:55296
	ds_read_b128 v[214:217], v193 offset:56320
	global_load_lds_dwordx4 v[218:219], off
	s_add_i32 m0, s33, 0x2000
	s_add_u32 s52, s52, 0x160080
	v_lshl_add_u64 v[218:219], v[220:221], 0, s[24:25]
	s_addc_u32 s53, s53, 0
	s_add_i32 s33, s73, s19
	global_load_lds_dwordx4 v[218:219], off
	v_lshl_add_u64 v[218:219], s[52:53], 0, v[154:155]
	s_mov_b32 m0, s33
	s_nop 0
	global_load_lds_dwordx4 v[218:219], off
	v_lshl_add_u64 v[218:219], s[52:53], 0, v[158:159]
	s_add_i32 m0, s33, 0x2000
	s_nop 0
	global_load_lds_dwordx4 v[218:219], off
	v_lshl_add_u64 v[218:219], v[222:223], 0, s[24:25]
	s_mov_b32 m0, s61
	s_nop 0
	global_load_lds_dwordx4 v[218:219], off
	v_lshl_add_u64 v[218:219], v[224:225], 0, s[24:25]
	s_mov_b32 m0, s62
	s_nop 0
	global_load_lds_dwordx4 v[218:219], off
	s_waitcnt vmcnt(8)
	s_waitcnt lgkmcnt(0)
	s_barrier
	s_waitcnt lgkmcnt(0)
	v_mfma_f32_16x16x32_bf16 v[60:63], v[128:131], v[176:179], v[60:63]
	v_mfma_f32_16x16x32_bf16 v[60:63], v[132:135], v[180:183], v[60:63]
	v_mfma_f32_16x16x32_bf16 v[56:59], v[136:139], v[176:179], v[56:59]
	v_mfma_f32_16x16x32_bf16 v[56:59], v[140:143], v[180:183], v[56:59]
	v_mfma_f32_16x16x32_bf16 v[44:47], v[128:131], v[184:187], v[44:47]
	v_mfma_f32_16x16x32_bf16 v[44:47], v[132:135], v[196:199], v[44:47]
	v_mfma_f32_16x16x32_bf16 v[40:43], v[136:139], v[184:187], v[40:43]
	v_mfma_f32_16x16x32_bf16 v[40:43], v[140:143], v[196:199], v[40:43]
	v_mfma_f32_16x16x32_bf16 v[28:31], v[128:131], v[200:203], v[28:31]
	v_mfma_f32_16x16x32_bf16 v[28:31], v[132:135], v[204:207], v[28:31]
	v_mfma_f32_16x16x32_bf16 v[24:27], v[136:139], v[200:203], v[24:27]
	v_mfma_f32_16x16x32_bf16 v[24:27], v[140:143], v[204:207], v[24:27]
	v_mfma_f32_16x16x32_bf16 v[12:15], v[128:131], v[208:211], v[12:15]
	v_mfma_f32_16x16x32_bf16 v[12:15], v[132:135], v[214:217], v[12:15]
	v_mfma_f32_16x16x32_bf16 v[8:11], v[136:139], v[208:211], v[8:11]
	v_mfma_f32_16x16x32_bf16 v[8:11], v[140:143], v[214:217], v[8:11]
	v_mfma_f32_16x16x32_bf16 v[52:55], v[144:147], v[176:179], v[52:55]
	v_mfma_f32_16x16x32_bf16 v[52:55], v[148:151], v[180:183], v[52:55]
	v_mfma_f32_16x16x32_bf16 v[48:51], v[168:171], v[176:179], v[48:51]
	v_mfma_f32_16x16x32_bf16 v[48:51], v[172:175], v[180:183], v[48:51]
	v_mfma_f32_16x16x32_bf16 v[36:39], v[144:147], v[184:187], v[36:39]
	v_mfma_f32_16x16x32_bf16 v[36:39], v[148:151], v[196:199], v[36:39]
	v_mfma_f32_16x16x32_bf16 v[32:35], v[168:171], v[184:187], v[32:35]
	v_mfma_f32_16x16x32_bf16 v[32:35], v[172:175], v[196:199], v[32:35]
	v_mfma_f32_16x16x32_bf16 v[20:23], v[144:147], v[200:203], v[20:23]
	v_mfma_f32_16x16x32_bf16 v[20:23], v[148:151], v[204:207], v[20:23]
	v_mfma_f32_16x16x32_bf16 v[16:19], v[168:171], v[200:203], v[16:19]
	v_mfma_f32_16x16x32_bf16 v[16:19], v[172:175], v[204:207], v[16:19]
	v_mfma_f32_16x16x32_bf16 v[4:7], v[144:147], v[208:211], v[4:7]
	v_mfma_f32_16x16x32_bf16 v[4:7], v[148:151], v[214:217], v[4:7]
	v_mfma_f32_16x16x32_bf16 v[0:3], v[168:171], v[208:211], v[0:3]
	v_mfma_f32_16x16x32_bf16 v[0:3], v[172:175], v[214:217], v[0:3]
	s_barrier
	s_add_i32 s72, s72, 2
	s_add_u32 s50, s50, 0x100
	s_addc_u32 s51, s51, 0
	s_add_u32 s34, s34, 0x100
	s_addc_u32 s35, s35, 0
	s_cmpk_gt_u32 s72, 0x55
	s_cbranch_scc0 .LBB0_335
	s_and_b64 vcc, exec, s[44:45]
	s_cbranch_vccz .LBB0_338
	s_barrier

; #define PG8_STAGE(bufoff, gbase, voff) do { _Pragma("unroll") for (int _i = 0; _i < 2; ++_i) \
;         __builtin_amdgcn_global_load_lds((const unsigned*)((const char*)(gbase) + (voff)[_i]), (PG8_LAS unsigned*)(lds + (bufoff) + ldsw + _i * 8192), 16, 0, 0); } while (0)
; #define PG8_WAIT_V(n) asm volatile("s_waitcnt vmcnt(" #n ")" ::: "memory")
; #define PG8_WAIT_L(n) asm volatile("s_waitcnt lgkmcnt(" #n ")" ::: "memory")
; #define PG8_BAR __builtin_amdgcn_s_barrier()
; #define PG8_SCHED __builtin_amdgcn_sched_barrier(0)
;     ...
;             const char* a1 = cA + (size_t)(t + 1) * kstep;
;             const char* a2 = last ? nA : cA + (size_t)(t + 2) * kstep; const char* b2 = last ? nB : cB + (size_t)(t + 2) * kstep;
;             const char* a3 = a2 + kstep; const char* b3 = b2 + kstep;
;             if (last && has_next) S.a_ready(nxt);
;             if (last) E.pre(pre, cur, wr, fr);
;             if constexpr (MIDK > 0) { if (t == MIDK / BK) E.mid(acc, cur, wr, wc, fr, fq); }
;             if constexpr (SP2) {
;             PG8_LDB(B0, 0, 0); PG8_LDB(B1, 0, 1); PG8_SCHED; PG8_LDA(At, 0, 0); PG8_STAGE(PG8_SA(1, 1), a1 + hstep, voffA);
;             PG8_WAIT_V(8); PG8_WAIT_L(0); PG8_BAR; PG8_MMA(0, 0, At, B0); PG8_MMA(0, 1, At, B1); PG8_BAR; PG8_SCHED;
;             PG8_LDA(At, 0, 1); PG8_STAGE(PG8_SB(0, 0), b2, voffB); PG8_STAGE(PG8_SB(0, 1), b2 + hstep, voffB); PG8_STAGE(PG8_SA(0, 0), a2, voffA);
;             PG8_WAIT_V(8); PG8_WAIT_L(0); PG8_BAR; PG8_MMA(1, 0, At, B0); PG8_MMA(1, 1, At, B1); PG8_BAR; PG8_SCHED;
.LBB0_432:
	v_add_u32_e32 v142, s91, v205
	v_add_u32_e32 v146, s92, v205
	ds_read_b128 v[130:133], v142
	ds_read_b128 v[134:137], v142 offset:1024
	s_waitcnt lgkmcnt(0)
	ds_read_b128 v[138:141], v142 offset:2048
	ds_read_b128 v[142:145], v142 offset:3072
	ds_read_b128 v[188:191], v146
	ds_read_b128 v[192:195], v146 offset:1024
	ds_read_b128 v[196:199], v146 offset:2048
	ds_read_b128 v[200:203], v146 offset:3072
	s_add_u32 s33, s70, 0xfff80080
	s_addc_u32 s74, s71, -1
	s_and_b64 s[72:73], s[72:73], exec
	s_cselect_b32 s75, s18, s74
	s_cselect_b32 s74, s19, s33
	s_cselect_b32 s73, s34, s61
	s_cselect_b32 s72, s35, s10
	v_lshl_add_u64 v[146:147], s[70:71], 0, v[162:163]
	s_add_i32 m0, s69, 0xc000
	ds_read_b128 v[214:217], v159
	ds_read_b128 v[218:221], v159 offset:1024
	ds_read_b128 v[222:225], v159 offset:2048
	ds_read_b128 v[226:229], v159 offset:3072
	ds_read_b128 v[230:233], v159 offset:4096
	ds_read_b128 v[234:237], v159 offset:5120
	ds_read_b128 v[238:241], v159 offset:6144
	ds_read_b128 v[242:245], v159 offset:7168
	global_load_lds_dwordx4 v[146:147], off
	v_lshl_add_u64 v[146:147], s[70:71], 0, v[164:165]
	s_add_i32 m0, s69, 0xe000
	s_nop 0
	global_load_lds_dwordx4 v[146:147], off
	s_waitcnt vmcnt(8)
	s_waitcnt lgkmcnt(0)
	s_barrier
	s_waitcnt lgkmcnt(0)
	v_mfma_f32_16x16x32_bf16 v[124:127], v[130:133], v[214:217], v[124:127]
	v_mfma_f32_16x16x32_bf16 v[124:127], v[134:137], v[218:221], v[124:127]
	v_mfma_f32_16x16x32_bf16 v[120:123], v[138:141], v[214:217], v[120:123]
	v_mfma_f32_16x16x32_bf16 v[120:123], v[142:145], v[218:221], v[120:123]
	v_mfma_f32_16x16x32_bf16 v[108:111], v[130:133], v[222:225], v[108:111]
	v_mfma_f32_16x16x32_bf16 v[108:111], v[134:137], v[226:229], v[108:111]
	v_mfma_f32_16x16x32_bf16 v[104:107], v[138:141], v[222:225], v[104:107]
	v_mfma_f32_16x16x32_bf16 v[104:107], v[142:145], v[226:229], v[104:107]
	v_mfma_f32_16x16x32_bf16 v[92:95], v[130:133], v[230:233], v[92:95]
	v_mfma_f32_16x16x32_bf16 v[92:95], v[134:137], v[234:237], v[92:95]
	v_mfma_f32_16x16x32_bf16 v[88:91], v[138:141], v[230:233], v[88:91]
	v_mfma_f32_16x16x32_bf16 v[88:91], v[142:145], v[234:237], v[88:91]
	v_mfma_f32_16x16x32_bf16 v[76:79], v[130:133], v[238:241], v[76:79]
	v_mfma_f32_16x16x32_bf16 v[76:79], v[134:137], v[242:245], v[76:79]
	v_mfma_f32_16x16x32_bf16 v[72:75], v[138:141], v[238:241], v[72:75]
	v_mfma_f32_16x16x32_bf16 v[72:75], v[142:145], v[242:245], v[72:75]
	v_mfma_f32_16x16x32_bf16 v[116:119], v[188:191], v[214:217], v[116:119]
	v_mfma_f32_16x16x32_bf16 v[116:119], v[192:195], v[218:221], v[116:119]
	v_mfma_f32_16x16x32_bf16 v[112:115], v[196:199], v[214:217], v[112:115]
	v_mfma_f32_16x16x32_bf16 v[112:115], v[200:203], v[218:221], v[112:115]
	v_mfma_f32_16x16x32_bf16 v[100:103], v[188:191], v[222:225], v[100:103]
	v_mfma_f32_16x16x32_bf16 v[100:103], v[192:195], v[226:229], v[100:103]
	v_mfma_f32_16x16x32_bf16 v[96:99], v[196:199], v[222:225], v[96:99]
	v_mfma_f32_16x16x32_bf16 v[96:99], v[200:203], v[226:229], v[96:99]
	v_mfma_f32_16x16x32_bf16 v[84:87], v[188:191], v[230:233], v[84:87]
	v_mfma_f32_16x16x32_bf16 v[84:87], v[192:195], v[234:237], v[84:87]
	v_mfma_f32_16x16x32_bf16 v[80:83], v[196:199], v[230:233], v[80:83]
	v_mfma_f32_16x16x32_bf16 v[80:83], v[200:203], v[234:237], v[80:83]
	v_mfma_f32_16x16x32_bf16 v[68:71], v[188:191], v[238:241], v[68:71]
	v_mfma_f32_16x16x32_bf16 v[68:71], v[192:195], v[242:245], v[68:71]
	v_mfma_f32_16x16x32_bf16 v[64:67], v[196:199], v[238:241], v[64:67]
	v_mfma_f32_16x16x32_bf16 v[64:67], v[200:203], v[242:245], v[64:67]
	s_barrier
	s_add_i32 s33, s91, s82
	v_lshl_add_u64 v[146:147], s[72:73], 0, v[150:151]
	s_mov_b32 m0, s33
	ds_read_b128 v[214:217], v159 offset:16384
	ds_read_b128 v[218:221], v159 offset:17408
	ds_read_b128 v[222:225], v159 offset:18432
	ds_read_b128 v[226:229], v159 offset:19456
	ds_read_b128 v[230:233], v159 offset:20480
	ds_read_b128 v[234:237], v159 offset:21504
	ds_read_b128 v[238:241], v159 offset:22528
	ds_read_b128 v[242:245], v159 offset:23552
	global_load_lds_dwordx4 v[146:147], off
	s_add_i32 m0, s33, 0x2000
	s_add_u32 s94, s72, 0x80000
	v_lshl_add_u64 v[246:247], s[72:73], 0, v[154:155]
	s_addc_u32 s95, s73, 0
	s_add_i32 s33, s92, s82
	global_load_lds_dwordx4 v[246:247], off
	v_lshl_add_u64 v[248:249], s[94:95], 0, v[150:151]
	s_mov_b32 m0, s33
	v_lshl_add_u64 v[250:251], s[74:75], 0, v[152:153]
	global_load_lds_dwordx4 v[248:249], off
	v_lshl_add_u64 v[248:249], s[94:95], 0, v[154:155]
	s_add_i32 m0, s33, 0x2000
	s_nop 0
	global_load_lds_dwordx4 v[248:249], off
	v_lshl_add_u64 v[248:249], s[74:75], 0, v[148:149]
	s_mov_b32 m0, s69
	s_nop 0
	global_load_lds_dwordx4 v[248:249], off
	s_mov_b32 m0, s83
	s_nop 0
	global_load_lds_dwordx4 v[250:251], off
	s_waitcnt vmcnt(8)
	s_waitcnt lgkmcnt(0)
	s_barrier
; #define PG8_STAGE(bufoff, gbase, voff) do { _Pragma("unroll") for (int _i = 0; _i < 2; ++_i) \
;         __builtin_amdgcn_global_load_lds((const unsigned*)((const char*)(gbase) + (voff)[_i]), (PG8_LAS unsigned*)(lds + (bufoff) + ldsw + _i * 8192), 16, 0, 0); } while (0)
; #define PG8_WAIT_V(n) asm volatile("s_waitcnt vmcnt(" #n ")" ::: "memory")
; #define PG8_WAIT_L(n) asm volatile("s_waitcnt lgkmcnt(" #n ")" ::: "memory")
; #define PG8_BAR __builtin_amdgcn_s_barrier()
; #define PG8_SCHED __builtin_amdgcn_sched_barrier(0)
;     ...
;             PG8_WAIT_V(8); PG8_WAIT_L(0); PG8_BAR; PG8_MMA(1, 0, At, B0); PG8_MMA(1, 1, At, B1); PG8_BAR; PG8_SCHED;
;             PG8_LDB(B0, 1, 0); PG8_LDB(B1, 1, 1); PG8_SCHED; PG8_LDA(At, 1, 0); PG8_STAGE(PG8_SA(0, 1), a2 + hstep, voffA);
;             PG8_WAIT_V(8); PG8_WAIT_L(0); PG8_BAR; PG8_MMA(0, 0, At, B0); PG8_MMA(0, 1, At, B1); PG8_BAR; PG8_SCHED;
	s_waitcnt lgkmcnt(0)
	v_mfma_f32_16x16x32_bf16 v[60:63], v[130:133], v[214:217], v[60:63]
	v_mfma_f32_16x16x32_bf16 v[60:63], v[134:137], v[218:221], v[60:63]
	v_mfma_f32_16x16x32_bf16 v[56:59], v[138:141], v[214:217], v[56:59]
	v_mfma_f32_16x16x32_bf16 v[56:59], v[142:145], v[218:221], v[56:59]
	v_mfma_f32_16x16x32_bf16 v[44:47], v[130:133], v[222:225], v[44:47]
	v_mfma_f32_16x16x32_bf16 v[44:47], v[134:137], v[226:229], v[44:47]
	v_mfma_f32_16x16x32_bf16 v[40:43], v[138:141], v[222:225], v[40:43]
	v_mfma_f32_16x16x32_bf16 v[40:43], v[142:145], v[226:229], v[40:43]
	v_mfma_f32_16x16x32_bf16 v[28:31], v[130:133], v[230:233], v[28:31]
	v_mfma_f32_16x16x32_bf16 v[28:31], v[134:137], v[234:237], v[28:31]
	v_mfma_f32_16x16x32_bf16 v[24:27], v[138:141], v[230:233], v[24:27]
	v_mfma_f32_16x16x32_bf16 v[24:27], v[142:145], v[234:237], v[24:27]
	v_mfma_f32_16x16x32_bf16 v[12:15], v[130:133], v[238:241], v[12:15]
	v_mfma_f32_16x16x32_bf16 v[12:15], v[134:137], v[242:245], v[12:15]
	v_mfma_f32_16x16x32_bf16 v[8:11], v[138:141], v[238:241], v[8:11]
	v_mfma_f32_16x16x32_bf16 v[8:11], v[142:145], v[242:245], v[8:11]
	v_mfma_f32_16x16x32_bf16 v[52:55], v[188:191], v[214:217], v[52:55]
	v_mfma_f32_16x16x32_bf16 v[52:55], v[192:195], v[218:221], v[52:55]
	v_mfma_f32_16x16x32_bf16 v[48:51], v[196:199], v[214:217], v[48:51]
	v_mfma_f32_16x16x32_bf16 v[48:51], v[200:203], v[218:221], v[48:51]
	v_mfma_f32_16x16x32_bf16 v[36:39], v[188:191], v[222:225], v[36:39]
	v_mfma_f32_16x16x32_bf16 v[36:39], v[192:195], v[226:229], v[36:39]
	v_mfma_f32_16x16x32_bf16 v[32:35], v[196:199], v[222:225], v[32:35]
	v_mfma_f32_16x16x32_bf16 v[32:35], v[200:203], v[226:229], v[32:35]
	v_mfma_f32_16x16x32_bf16 v[20:23], v[188:191], v[230:233], v[20:23]
	v_mfma_f32_16x16x32_bf16 v[20:23], v[192:195], v[234:237], v[20:23]
	v_mfma_f32_16x16x32_bf16 v[16:19], v[196:199], v[230:233], v[16:19]
	v_mfma_f32_16x16x32_bf16 v[16:19], v[200:203], v[234:237], v[16:19]
	v_mfma_f32_16x16x32_bf16 v[4:7], v[188:191], v[238:241], v[4:7]
	v_mfma_f32_16x16x32_bf16 v[4:7], v[192:195], v[242:245], v[4:7]
	v_mfma_f32_16x16x32_bf16 v[0:3], v[196:199], v[238:241], v[0:3]
	v_mfma_f32_16x16x32_bf16 v[0:3], v[200:203], v[242:245], v[0:3]
	s_barrier
	s_add_i32 s33, 0, 0x18000
	s_add_i32 s94, 0, 0x1c000
	v_add_u32_e32 v142, s33, v205
	v_add_u32_e32 v156, s94, v205
	ds_read_b128 v[130:133], v142
	ds_read_b128 v[134:137], v142 offset:1024
	ds_read_b128 v[138:141], v142 offset:2048
	ds_read_b128 v[142:145], v142 offset:3072
	ds_read_b128 v[188:191], v156
	ds_read_b128 v[192:195], v156 offset:1024
	ds_read_b128 v[196:199], v156 offset:2048
	ds_read_b128 v[200:203], v156 offset:3072
	s_add_u32 s74, s74, 0x80000
	s_addc_u32 s75, s75, 0
	s_mov_b32 m0, s84
	v_lshl_add_u64 v[252:253], s[74:75], 0, v[148:149]
	ds_read_b128 v[214:217], v159 offset:32768
	ds_read_b128 v[218:221], v159 offset:33792
	ds_read_b128 v[222:225], v159 offset:34816
	ds_read_b128 v[226:229], v159 offset:35840
	ds_read_b128 v[230:233], v159 offset:36864
	ds_read_b128 v[234:237], v159 offset:37888
	ds_read_b128 v[238:241], v159 offset:38912
	ds_read_b128 v[242:245], v159 offset:39936
	global_load_lds_dwordx4 v[252:253], off
	v_lshl_add_u64 v[252:253], s[74:75], 0, v[152:153]
	s_mov_b32 m0, s85
	s_nop 0
	global_load_lds_dwordx4 v[252:253], off
	s_waitcnt vmcnt(8)
	s_waitcnt lgkmcnt(0)
	s_barrier
	s_waitcnt lgkmcnt(0)
	v_mfma_f32_16x16x32_bf16 v[124:127], v[130:133], v[214:217], v[124:127]
	v_mfma_f32_16x16x32_bf16 v[124:127], v[134:137], v[218:221], v[124:127]
	v_mfma_f32_16x16x32_bf16 v[120:123], v[138:141], v[214:217], v[120:123]
	v_mfma_f32_16x16x32_bf16 v[120:123], v[142:145], v[218:221], v[120:123]
	v_mfma_f32_16x16x32_bf16 v[108:111], v[130:133], v[222:225], v[108:111]
	v_mfma_f32_16x16x32_bf16 v[108:111], v[134:137], v[226:229], v[108:111]
	v_mfma_f32_16x16x32_bf16 v[104:107], v[138:141], v[222:225], v[104:107]
	v_mfma_f32_16x16x32_bf16 v[104:107], v[142:145], v[226:229], v[104:107]
	v_mfma_f32_16x16x32_bf16 v[92:95], v[130:133], v[230:233], v[92:95]
	v_mfma_f32_16x16x32_bf16 v[92:95], v[134:137], v[234:237], v[92:95]
	v_mfma_f32_16x16x32_bf16 v[88:91], v[138:141], v[230:233], v[88:91]
	v_mfma_f32_16x16x32_bf16 v[88:91], v[142:145], v[234:237], v[88:91]
	v_mfma_f32_16x16x32_bf16 v[76:79], v[130:133], v[238:241], v[76:79]
	v_mfma_f32_16x16x32_bf16 v[76:79], v[134:137], v[242:245], v[76:79]
	v_mfma_f32_16x16x32_bf16 v[72:75], v[138:141], v[238:241], v[72:75]
	v_mfma_f32_16x16x32_bf16 v[72:75], v[142:145], v[242:245], v[72:75]
	v_mfma_f32_16x16x32_bf16 v[116:119], v[188:191], v[214:217], v[116:119]
	v_mfma_f32_16x16x32_bf16 v[116:119], v[192:195], v[218:221], v[116:119]
	v_mfma_f32_16x16x32_bf16 v[112:115], v[196:199], v[214:217], v[112:115]
	v_mfma_f32_16x16x32_bf16 v[112:115], v[200:203], v[218:221], v[112:115]
	v_mfma_f32_16x16x32_bf16 v[100:103], v[188:191], v[222:225], v[100:103]
	v_mfma_f32_16x16x32_bf16 v[100:103], v[192:195], v[226:229], v[100:103]
	v_mfma_f32_16x16x32_bf16 v[96:99], v[196:199], v[222:225], v[96:99]
	v_mfma_f32_16x16x32_bf16 v[96:99], v[200:203], v[226:229], v[96:99]
	v_mfma_f32_16x16x32_bf16 v[84:87], v[188:191], v[230:233], v[84:87]
	v_mfma_f32_16x16x32_bf16 v[84:87], v[192:195], v[234:237], v[84:87]
	v_mfma_f32_16x16x32_bf16 v[80:83], v[196:199], v[230:233], v[80:83]
	v_mfma_f32_16x16x32_bf16 v[80:83], v[200:203], v[234:237], v[80:83]
	v_mfma_f32_16x16x32_bf16 v[68:71], v[188:191], v[238:241], v[68:71]
	v_mfma_f32_16x16x32_bf16 v[68:71], v[192:195], v[242:245], v[68:71]
	v_mfma_f32_16x16x32_bf16 v[64:67], v[196:199], v[238:241], v[64:67]
	v_mfma_f32_16x16x32_bf16 v[64:67], v[200:203], v[242:245], v[64:67]
	s_barrier
; #define PG8_STAGE(bufoff, gbase, voff) do { _Pragma("unroll") for (int _i = 0; _i < 2; ++_i) \
;         __builtin_amdgcn_global_load_lds((const unsigned*)((const char*)(gbase) + (voff)[_i]), (PG8_LAS unsigned*)(lds + (bufoff) + ldsw + _i * 8192), 16, 0, 0); } while (0)
; #define PG8_WAIT_V(n) asm volatile("s_waitcnt vmcnt(" #n ")" ::: "memory")
; #define PG8_WAIT_L(n) asm volatile("s_waitcnt lgkmcnt(" #n ")" ::: "memory")
; #define PG8_BAR __builtin_amdgcn_s_barrier()
; #define PG8_SCHED __builtin_amdgcn_sched_barrier(0)
;     ...
;         for (int t = 0; t < nt; t += 2) {
;     ...
;             PG8_LDA(At, 1, 1); PG8_STAGE(PG8_SB(1, 0), b3, voffB); PG8_STAGE(PG8_SB(1, 1), b3 + hstep, voffB); PG8_STAGE(PG8_SA(1, 0), a3, voffA);
;             PG8_WAIT_V(8); PG8_WAIT_L(0); PG8_BAR; PG8_MMA(1, 0, At, B0); PG8_MMA(1, 1, At, B1); PG8_BAR; PG8_SCHED;
	s_add_i32 s33, s33, s82
	v_lshl_add_u64 v[146:147], v[146:147], 0, s[50:51]
	s_mov_b32 m0, s33
	ds_read_b128 v[214:217], v159 offset:49152
	ds_read_b128 v[218:221], v159 offset:50176
	ds_read_b128 v[222:225], v159 offset:51200
	ds_read_b128 v[226:229], v159 offset:52224
	ds_read_b128 v[230:233], v159 offset:53248
	ds_read_b128 v[234:237], v159 offset:54272
	ds_read_b128 v[238:241], v159 offset:55296
	ds_read_b128 v[242:245], v159 offset:56320
	global_load_lds_dwordx4 v[146:147], off
	s_add_i32 m0, s33, 0x2000
	s_add_u32 s72, s72, 0x80080
	v_lshl_add_u64 v[146:147], v[246:247], 0, s[50:51]
	s_addc_u32 s73, s73, 0
	s_add_i32 s33, s94, s82
	global_load_lds_dwordx4 v[146:147], off
	v_lshl_add_u64 v[146:147], s[72:73], 0, v[150:151]
	s_mov_b32 m0, s33
	s_nop 0
	global_load_lds_dwordx4 v[146:147], off
	v_lshl_add_u64 v[146:147], s[72:73], 0, v[154:155]
	s_add_i32 m0, s33, 0x2000
	s_nop 0
	global_load_lds_dwordx4 v[146:147], off
	v_lshl_add_u64 v[146:147], v[248:249], 0, s[50:51]
	s_mov_b32 m0, s86
	s_nop 0
	global_load_lds_dwordx4 v[146:147], off
	v_lshl_add_u64 v[146:147], v[250:251], 0, s[50:51]
	s_mov_b32 m0, s87
	s_nop 0
	global_load_lds_dwordx4 v[146:147], off
	s_waitcnt vmcnt(8)
	s_waitcnt lgkmcnt(0)
	s_barrier
	s_waitcnt lgkmcnt(0)
	v_mfma_f32_16x16x32_bf16 v[60:63], v[130:133], v[214:217], v[60:63]
	v_mfma_f32_16x16x32_bf16 v[60:63], v[134:137], v[218:221], v[60:63]
	v_mfma_f32_16x16x32_bf16 v[56:59], v[138:141], v[214:217], v[56:59]
	v_mfma_f32_16x16x32_bf16 v[56:59], v[142:145], v[218:221], v[56:59]
	v_mfma_f32_16x16x32_bf16 v[44:47], v[130:133], v[222:225], v[44:47]
	v_mfma_f32_16x16x32_bf16 v[44:47], v[134:137], v[226:229], v[44:47]
	v_mfma_f32_16x16x32_bf16 v[40:43], v[138:141], v[222:225], v[40:43]
	v_mfma_f32_16x16x32_bf16 v[40:43], v[142:145], v[226:229], v[40:43]
	v_mfma_f32_16x16x32_bf16 v[28:31], v[130:133], v[230:233], v[28:31]
	v_mfma_f32_16x16x32_bf16 v[28:31], v[134:137], v[234:237], v[28:31]
	v_mfma_f32_16x16x32_bf16 v[24:27], v[138:141], v[230:233], v[24:27]
	v_mfma_f32_16x16x32_bf16 v[24:27], v[142:145], v[234:237], v[24:27]
	v_mfma_f32_16x16x32_bf16 v[12:15], v[130:133], v[238:241], v[12:15]
	v_mfma_f32_16x16x32_bf16 v[12:15], v[134:137], v[242:245], v[12:15]
	v_mfma_f32_16x16x32_bf16 v[8:11], v[138:141], v[238:241], v[8:11]
	v_mfma_f32_16x16x32_bf16 v[8:11], v[142:145], v[242:245], v[8:11]
	v_mfma_f32_16x16x32_bf16 v[52:55], v[188:191], v[214:217], v[52:55]
	v_mfma_f32_16x16x32_bf16 v[52:55], v[192:195], v[218:221], v[52:55]
	v_mfma_f32_16x16x32_bf16 v[48:51], v[196:199], v[214:217], v[48:51]
	v_mfma_f32_16x16x32_bf16 v[48:51], v[200:203], v[218:221], v[48:51]
	v_mfma_f32_16x16x32_bf16 v[36:39], v[188:191], v[222:225], v[36:39]
	v_mfma_f32_16x16x32_bf16 v[36:39], v[192:195], v[226:229], v[36:39]
	v_mfma_f32_16x16x32_bf16 v[32:35], v[196:199], v[222:225], v[32:35]
	v_mfma_f32_16x16x32_bf16 v[32:35], v[200:203], v[226:229], v[32:35]
	v_mfma_f32_16x16x32_bf16 v[20:23], v[188:191], v[230:233], v[20:23]
	v_mfma_f32_16x16x32_bf16 v[20:23], v[192:195], v[234:237], v[20:23]
	v_mfma_f32_16x16x32_bf16 v[16:19], v[196:199], v[230:233], v[16:19]
	v_mfma_f32_16x16x32_bf16 v[16:19], v[200:203], v[234:237], v[16:19]
	v_mfma_f32_16x16x32_bf16 v[4:7], v[188:191], v[238:241], v[4:7]
	v_mfma_f32_16x16x32_bf16 v[4:7], v[192:195], v[242:245], v[4:7]
	v_mfma_f32_16x16x32_bf16 v[0:3], v[196:199], v[238:241], v[0:3]
	v_mfma_f32_16x16x32_bf16 v[0:3], v[200:203], v[242:245], v[0:3]
	s_barrier
	s_add_i32 s63, s63, 2
	s_add_u32 s70, s70, 0x100
	s_addc_u32 s71, s71, 0
	s_add_u32 s10, s10, 0x100
	s_addc_u32 s61, s61, 0
	s_cmp_gt_u32 s63, 29
	s_cbranch_scc1 .LBB0_435

; #define PG8_STAGE(bufoff, gbase, voff) do { _Pragma("unroll") for (int _i = 0; _i < 2; ++_i) \
;         __builtin_amdgcn_global_load_lds((const unsigned*)((const char*)(gbase) + (voff)[_i]), (PG8_LAS unsigned*)(lds + (bufoff) + ldsw + _i * 8192), 16, 0, 0); } while (0)
; #define PG8_WAIT_V(n) asm volatile("s_waitcnt vmcnt(" #n ")" ::: "memory")
; #define PG8_WAIT_L(n) asm volatile("s_waitcnt lgkmcnt(" #n ")" ::: "memory")
; #define PG8_BAR __builtin_amdgcn_s_barrier()
; #define PG8_SCHED __builtin_amdgcn_sched_barrier(0)
;     ...
;             PG8_LDB(B0, 0, 0); PG8_LDB(B1, 0, 1); PG8_SCHED; PG8_LDA(At, 0, 0); PG8_STAGE(PG8_SA(1, 1), a1 + hstep, voffA);
;             PG8_WAIT_V(8); PG8_WAIT_L(0); PG8_BAR; PG8_MMA(0, 0, At, B0); PG8_MMA(0, 1, At, B1); PG8_BAR; PG8_SCHED;
;             PG8_LDA(At, 0, 1); PG8_STAGE(PG8_SB(0, 0), b2, voffB); PG8_STAGE(PG8_SB(0, 1), b2 + hstep, voffB); PG8_STAGE(PG8_SA(0, 0), a2, voffA);
.LBB0_666:
	v_add_u32_e32 v1, s70, v175
	s_add_u32 s33, s52, s54
	ds_read_b128 v[140:143], v1
	ds_read_b128 v[144:147], v1 offset:1024
	ds_read_b128 v[148:151], v1 offset:2048
	ds_read_b128 v[152:155], v1 offset:3072
	v_add_u32_e32 v1, s71, v175
	s_addc_u32 s58, s53, s55
	ds_read_b128 v[190:193], v1
	ds_read_b128 v[194:197], v1 offset:1024
	ds_read_b128 v[198:201], v1 offset:2048
	ds_read_b128 v[202:205], v1 offset:3072
	s_add_u32 s33, s33, 0x100
	s_addc_u32 s76, s58, 0
	s_and_b64 s[58:59], s[56:57], exec
	s_cselect_b32 s59, s34, s76
	s_cselect_b32 s58, s35, s33
	s_add_u32 s33, s73, s54
	s_addc_u32 s76, s74, s55
	s_and_b64 s[56:57], s[56:57], exec
	s_cselect_b32 s57, s45, s76
	s_cselect_b32 s56, s47, s33
	v_lshl_add_u64 v[2:3], v[136:137], 0, s[54:55]
	s_add_i32 m0, s63, 0xc000
	ds_read_b128 v[206:209], v179
	ds_read_b128 v[214:217], v179 offset:1024
	ds_read_b128 v[218:221], v179 offset:2048
	ds_read_b128 v[222:225], v179 offset:3072
	ds_read_b128 v[226:229], v179 offset:4096
	ds_read_b128 v[230:233], v179 offset:5120
	ds_read_b128 v[234:237], v179 offset:6144
	ds_read_b128 v[238:241], v179 offset:7168
	global_load_lds_dwordx4 v[2:3], off
	v_lshl_add_u64 v[2:3], v[138:139], 0, s[54:55]
	s_add_i32 m0, s63, 0xe000
	s_nop 0
	global_load_lds_dwordx4 v[2:3], off
	s_waitcnt vmcnt(8)
	s_waitcnt lgkmcnt(0)
	s_barrier
	s_waitcnt lgkmcnt(0)
	v_mfma_f32_16x16x32_bf16 v[128:131], v[140:143], v[206:209], v[128:131]
	v_mfma_f32_16x16x32_bf16 v[128:131], v[144:147], v[214:217], v[128:131]
	v_mfma_f32_16x16x32_bf16 v[124:127], v[148:151], v[206:209], v[124:127]
	v_mfma_f32_16x16x32_bf16 v[124:127], v[152:155], v[214:217], v[124:127]
	v_mfma_f32_16x16x32_bf16 v[112:115], v[140:143], v[218:221], v[112:115]
	v_mfma_f32_16x16x32_bf16 v[112:115], v[144:147], v[222:225], v[112:115]
	v_mfma_f32_16x16x32_bf16 v[108:111], v[148:151], v[218:221], v[108:111]
	v_mfma_f32_16x16x32_bf16 v[108:111], v[152:155], v[222:225], v[108:111]
	v_mfma_f32_16x16x32_bf16 v[96:99], v[140:143], v[226:229], v[96:99]
	v_mfma_f32_16x16x32_bf16 v[96:99], v[144:147], v[230:233], v[96:99]
	v_mfma_f32_16x16x32_bf16 v[92:95], v[148:151], v[226:229], v[92:95]
	v_mfma_f32_16x16x32_bf16 v[92:95], v[152:155], v[230:233], v[92:95]
	v_mfma_f32_16x16x32_bf16 v[80:83], v[140:143], v[234:237], v[80:83]
	v_mfma_f32_16x16x32_bf16 v[80:83], v[144:147], v[238:241], v[80:83]
	v_mfma_f32_16x16x32_bf16 v[76:79], v[148:151], v[234:237], v[76:79]
	v_mfma_f32_16x16x32_bf16 v[76:79], v[152:155], v[238:241], v[76:79]
	v_mfma_f32_16x16x32_bf16 v[120:123], v[190:193], v[206:209], v[120:123]
	v_mfma_f32_16x16x32_bf16 v[120:123], v[194:197], v[214:217], v[120:123]
	v_mfma_f32_16x16x32_bf16 v[116:119], v[198:201], v[206:209], v[116:119]
	v_mfma_f32_16x16x32_bf16 v[116:119], v[202:205], v[214:217], v[116:119]
	v_mfma_f32_16x16x32_bf16 v[104:107], v[190:193], v[218:221], v[104:107]
	v_mfma_f32_16x16x32_bf16 v[104:107], v[194:197], v[222:225], v[104:107]
	v_mfma_f32_16x16x32_bf16 v[100:103], v[198:201], v[218:221], v[100:103]
	v_mfma_f32_16x16x32_bf16 v[100:103], v[202:205], v[222:225], v[100:103]
	v_mfma_f32_16x16x32_bf16 v[88:91], v[190:193], v[226:229], v[88:91]
	v_mfma_f32_16x16x32_bf16 v[88:91], v[194:197], v[230:233], v[88:91]
	v_mfma_f32_16x16x32_bf16 v[84:87], v[198:201], v[226:229], v[84:87]
	v_mfma_f32_16x16x32_bf16 v[84:87], v[202:205], v[230:233], v[84:87]
	v_mfma_f32_16x16x32_bf16 v[72:75], v[190:193], v[234:237], v[72:75]
	v_mfma_f32_16x16x32_bf16 v[72:75], v[194:197], v[238:241], v[72:75]
	v_mfma_f32_16x16x32_bf16 v[68:71], v[198:201], v[234:237], v[68:71]
	v_mfma_f32_16x16x32_bf16 v[68:71], v[202:205], v[238:241], v[68:71]
	s_barrier
	s_add_i32 s33, s70, s62
	v_lshl_add_u64 v[210:211], s[56:57], 0, v[158:159]
	s_mov_b32 m0, s33
	ds_read_b128 v[206:209], v179 offset:16384
	ds_read_b128 v[214:217], v179 offset:17408
	ds_read_b128 v[218:221], v179 offset:18432
	ds_read_b128 v[222:225], v179 offset:19456
	ds_read_b128 v[226:229], v179 offset:20480
	ds_read_b128 v[230:233], v179 offset:21504
	ds_read_b128 v[234:237], v179 offset:22528
	ds_read_b128 v[238:241], v179 offset:23552
	global_load_lds_dwordx4 v[210:211], off
	s_add_i32 m0, s33, 0x2000
	s_add_u32 s76, s56, 0x80000
	v_lshl_add_u64 v[242:243], s[56:57], 0, v[162:163]
	s_addc_u32 s77, s57, 0
	s_add_i32 s33, s71, s62
	global_load_lds_dwordx4 v[242:243], off
	v_lshl_add_u64 v[2:3], s[76:77], 0, v[158:159]
	s_mov_b32 m0, s33
	v_lshl_add_u64 v[244:245], s[58:59], 0, v[156:157]
	global_load_lds_dwordx4 v[2:3], off
	v_lshl_add_u64 v[2:3], s[76:77], 0, v[162:163]
	s_add_i32 m0, s33, 0x2000
	v_lshl_add_u64 v[246:247], s[58:59], 0, v[160:161]
	global_load_lds_dwordx4 v[2:3], off
	s_mov_b32 m0, s63
	s_nop 0
	global_load_lds_dwordx4 v[244:245], off
	s_mov_b32 m0, s64
	s_nop 0
	global_load_lds_dwordx4 v[246:247], off
	s_waitcnt vmcnt(8)
	s_waitcnt lgkmcnt(0)
	s_barrier
; #define PG8_STAGE(bufoff, gbase, voff) do { _Pragma("unroll") for (int _i = 0; _i < 2; ++_i) \
;         __builtin_amdgcn_global_load_lds((const unsigned*)((const char*)(gbase) + (voff)[_i]), (PG8_LAS unsigned*)(lds + (bufoff) + ldsw + _i * 8192), 16, 0, 0); } while (0)
; #define PG8_WAIT_V(n) asm volatile("s_waitcnt vmcnt(" #n ")" ::: "memory")
; #define PG8_WAIT_L(n) asm volatile("s_waitcnt lgkmcnt(" #n ")" ::: "memory")
; #define PG8_BAR __builtin_amdgcn_s_barrier()
; #define PG8_SCHED __builtin_amdgcn_sched_barrier(0)
;     ...
;             PG8_WAIT_V(8); PG8_WAIT_L(0); PG8_BAR; PG8_MMA(1, 0, At, B0); PG8_MMA(1, 1, At, B1); PG8_BAR; PG8_SCHED;
;             PG8_LDB(B0, 1, 0); PG8_LDB(B1, 1, 1); PG8_SCHED; PG8_LDA(At, 1, 0); PG8_STAGE(PG8_SA(0, 1), a2 + hstep, voffA);
;             PG8_WAIT_V(8); PG8_WAIT_L(0); PG8_BAR; PG8_MMA(0, 0, At, B0); PG8_MMA(0, 1, At, B1); PG8_BAR; PG8_SCHED;
	s_waitcnt lgkmcnt(0)
	v_mfma_f32_16x16x32_bf16 v[64:67], v[140:143], v[206:209], v[64:67]
	v_mfma_f32_16x16x32_bf16 v[64:67], v[144:147], v[214:217], v[64:67]
	v_mfma_f32_16x16x32_bf16 v[60:63], v[148:151], v[206:209], v[60:63]
	v_mfma_f32_16x16x32_bf16 v[60:63], v[152:155], v[214:217], v[60:63]
	v_mfma_f32_16x16x32_bf16 v[48:51], v[140:143], v[218:221], v[48:51]
	v_mfma_f32_16x16x32_bf16 v[48:51], v[144:147], v[222:225], v[48:51]
	v_mfma_f32_16x16x32_bf16 v[44:47], v[148:151], v[218:221], v[44:47]
	v_mfma_f32_16x16x32_bf16 v[44:47], v[152:155], v[222:225], v[44:47]
	v_mfma_f32_16x16x32_bf16 v[32:35], v[140:143], v[226:229], v[32:35]
	v_mfma_f32_16x16x32_bf16 v[32:35], v[144:147], v[230:233], v[32:35]
	v_mfma_f32_16x16x32_bf16 v[28:31], v[148:151], v[226:229], v[28:31]
	v_mfma_f32_16x16x32_bf16 v[28:31], v[152:155], v[230:233], v[28:31]
	v_mfma_f32_16x16x32_bf16 v[16:19], v[140:143], v[234:237], v[16:19]
	v_mfma_f32_16x16x32_bf16 v[16:19], v[144:147], v[238:241], v[16:19]
	v_mfma_f32_16x16x32_bf16 v[12:15], v[148:151], v[234:237], v[12:15]
	v_mfma_f32_16x16x32_bf16 v[12:15], v[152:155], v[238:241], v[12:15]
	v_mfma_f32_16x16x32_bf16 v[56:59], v[190:193], v[206:209], v[56:59]
	v_mfma_f32_16x16x32_bf16 v[56:59], v[194:197], v[214:217], v[56:59]
	v_mfma_f32_16x16x32_bf16 v[52:55], v[198:201], v[206:209], v[52:55]
	v_mfma_f32_16x16x32_bf16 v[52:55], v[202:205], v[214:217], v[52:55]
	v_mfma_f32_16x16x32_bf16 v[40:43], v[190:193], v[218:221], v[40:43]
	v_mfma_f32_16x16x32_bf16 v[40:43], v[194:197], v[222:225], v[40:43]
	v_mfma_f32_16x16x32_bf16 v[36:39], v[198:201], v[218:221], v[36:39]
	v_mfma_f32_16x16x32_bf16 v[36:39], v[202:205], v[222:225], v[36:39]
	v_mfma_f32_16x16x32_bf16 v[24:27], v[190:193], v[226:229], v[24:27]
	v_mfma_f32_16x16x32_bf16 v[24:27], v[194:197], v[230:233], v[24:27]
	v_mfma_f32_16x16x32_bf16 v[20:23], v[198:201], v[226:229], v[20:23]
	v_mfma_f32_16x16x32_bf16 v[20:23], v[202:205], v[230:233], v[20:23]
	v_mfma_f32_16x16x32_bf16 v[8:11], v[190:193], v[234:237], v[8:11]
	v_mfma_f32_16x16x32_bf16 v[8:11], v[194:197], v[238:241], v[8:11]
	v_mfma_f32_16x16x32_bf16 v[2:5], v[198:201], v[234:237], v[4:7]
	v_mfma_f32_16x16x32_bf16 v[2:5], v[202:205], v[238:241], v[2:5]
	s_barrier
	s_add_i32 s33, 0, 0x18000
	v_add_u32_e32 v1, s33, v175
	s_add_i32 s76, 0, 0x1c000
	ds_read_b128 v[140:143], v1
	ds_read_b128 v[144:147], v1 offset:1024
	ds_read_b128 v[148:151], v1 offset:2048
	ds_read_b128 v[152:155], v1 offset:3072
	v_add_u32_e32 v1, s76, v175
	ds_read_b128 v[190:193], v1
	ds_read_b128 v[194:197], v1 offset:1024
	ds_read_b128 v[198:201], v1 offset:2048
	ds_read_b128 v[202:205], v1 offset:3072
	s_add_u32 s58, s58, 0x80000
	s_addc_u32 s59, s59, 0
	s_mov_b32 m0, s65
	v_lshl_add_u64 v[6:7], s[58:59], 0, v[156:157]
	ds_read_b128 v[206:209], v179 offset:32768
	ds_read_b128 v[214:217], v179 offset:33792
	ds_read_b128 v[218:221], v179 offset:34816
	ds_read_b128 v[222:225], v179 offset:35840
	ds_read_b128 v[226:229], v179 offset:36864
	ds_read_b128 v[230:233], v179 offset:37888
	ds_read_b128 v[234:237], v179 offset:38912
	ds_read_b128 v[238:241], v179 offset:39936
	global_load_lds_dwordx4 v[6:7], off
	v_lshl_add_u64 v[6:7], s[58:59], 0, v[160:161]
	s_mov_b32 m0, s66
	s_nop 0
	global_load_lds_dwordx4 v[6:7], off
	s_waitcnt vmcnt(8)
	s_waitcnt lgkmcnt(0)
	s_barrier
	s_waitcnt lgkmcnt(0)
	v_mfma_f32_16x16x32_bf16 v[128:131], v[140:143], v[206:209], v[128:131]
	v_mfma_f32_16x16x32_bf16 v[128:131], v[144:147], v[214:217], v[128:131]
	v_mfma_f32_16x16x32_bf16 v[124:127], v[148:151], v[206:209], v[124:127]
	v_mfma_f32_16x16x32_bf16 v[124:127], v[152:155], v[214:217], v[124:127]
	v_mfma_f32_16x16x32_bf16 v[112:115], v[140:143], v[218:221], v[112:115]
	v_mfma_f32_16x16x32_bf16 v[112:115], v[144:147], v[222:225], v[112:115]
	v_mfma_f32_16x16x32_bf16 v[108:111], v[148:151], v[218:221], v[108:111]
	v_mfma_f32_16x16x32_bf16 v[108:111], v[152:155], v[222:225], v[108:111]
	v_mfma_f32_16x16x32_bf16 v[96:99], v[140:143], v[226:229], v[96:99]
	v_mfma_f32_16x16x32_bf16 v[96:99], v[144:147], v[230:233], v[96:99]
	v_mfma_f32_16x16x32_bf16 v[92:95], v[148:151], v[226:229], v[92:95]
	v_mfma_f32_16x16x32_bf16 v[92:95], v[152:155], v[230:233], v[92:95]
	v_mfma_f32_16x16x32_bf16 v[80:83], v[140:143], v[234:237], v[80:83]
	v_mfma_f32_16x16x32_bf16 v[80:83], v[144:147], v[238:241], v[80:83]
	v_mfma_f32_16x16x32_bf16 v[76:79], v[148:151], v[234:237], v[76:79]
	v_mfma_f32_16x16x32_bf16 v[76:79], v[152:155], v[238:241], v[76:79]
	v_mfma_f32_16x16x32_bf16 v[120:123], v[190:193], v[206:209], v[120:123]
	v_mfma_f32_16x16x32_bf16 v[120:123], v[194:197], v[214:217], v[120:123]
	v_mfma_f32_16x16x32_bf16 v[116:119], v[198:201], v[206:209], v[116:119]
	v_mfma_f32_16x16x32_bf16 v[116:119], v[202:205], v[214:217], v[116:119]
	v_mfma_f32_16x16x32_bf16 v[104:107], v[190:193], v[218:221], v[104:107]
	v_mfma_f32_16x16x32_bf16 v[104:107], v[194:197], v[222:225], v[104:107]
	v_mfma_f32_16x16x32_bf16 v[100:103], v[198:201], v[218:221], v[100:103]
	v_mfma_f32_16x16x32_bf16 v[100:103], v[202:205], v[222:225], v[100:103]
	v_mfma_f32_16x16x32_bf16 v[88:91], v[190:193], v[226:229], v[88:91]
	v_mfma_f32_16x16x32_bf16 v[88:91], v[194:197], v[230:233], v[88:91]
	v_mfma_f32_16x16x32_bf16 v[84:87], v[198:201], v[226:229], v[84:87]
	v_mfma_f32_16x16x32_bf16 v[84:87], v[202:205], v[230:233], v[84:87]
	v_mfma_f32_16x16x32_bf16 v[72:75], v[190:193], v[234:237], v[72:75]
	v_mfma_f32_16x16x32_bf16 v[72:75], v[194:197], v[238:241], v[72:75]
	v_mfma_f32_16x16x32_bf16 v[68:71], v[198:201], v[234:237], v[68:71]
	v_mfma_f32_16x16x32_bf16 v[68:71], v[202:205], v[238:241], v[68:71]
	s_barrier
; #define PG8_STAGE(bufoff, gbase, voff) do { _Pragma("unroll") for (int _i = 0; _i < 2; ++_i) \
;         __builtin_amdgcn_global_load_lds((const unsigned*)((const char*)(gbase) + (voff)[_i]), (PG8_LAS unsigned*)(lds + (bufoff) + ldsw + _i * 8192), 16, 0, 0); } while (0)
; #define PG8_WAIT_V(n) asm volatile("s_waitcnt vmcnt(" #n ")" ::: "memory")
; #define PG8_WAIT_L(n) asm volatile("s_waitcnt lgkmcnt(" #n ")" ::: "memory")
; #define PG8_BAR __builtin_amdgcn_s_barrier()
; #define PG8_SCHED __builtin_amdgcn_sched_barrier(0)
;     ...
;             PG8_LDA(At, 1, 1); PG8_STAGE(PG8_SB(1, 0), b3, voffB); PG8_STAGE(PG8_SB(1, 1), b3 + hstep, voffB); PG8_STAGE(PG8_SA(1, 0), a3, voffA);
;             PG8_WAIT_V(8); PG8_WAIT_L(0); PG8_BAR; PG8_MMA(1, 0, At, B0); PG8_MMA(1, 1, At, B1); PG8_BAR; PG8_SCHED;
	s_add_i32 s33, s33, s62
	v_lshl_add_u64 v[6:7], v[210:211], 0, s[40:41]
	s_mov_b32 m0, s33
	ds_read_b128 v[206:209], v179 offset:49152
	ds_read_b128 v[214:217], v179 offset:50176
	ds_read_b128 v[218:221], v179 offset:51200
	ds_read_b128 v[222:225], v179 offset:52224
	ds_read_b128 v[226:229], v179 offset:53248
	ds_read_b128 v[230:233], v179 offset:54272
	ds_read_b128 v[234:237], v179 offset:55296
	ds_read_b128 v[238:241], v179 offset:56320
	global_load_lds_dwordx4 v[6:7], off
	s_add_i32 m0, s33, 0x2000
	s_add_u32 s56, s56, 0x80080
	v_lshl_add_u64 v[6:7], v[242:243], 0, s[40:41]
	s_addc_u32 s57, s57, 0
	s_add_i32 s33, s76, s62
	global_load_lds_dwordx4 v[6:7], off
	v_lshl_add_u64 v[6:7], s[56:57], 0, v[158:159]
	s_mov_b32 m0, s33
	s_nop 0
	global_load_lds_dwordx4 v[6:7], off
	v_lshl_add_u64 v[6:7], s[56:57], 0, v[162:163]
	s_add_i32 m0, s33, 0x2000
	s_nop 0
	global_load_lds_dwordx4 v[6:7], off
	v_lshl_add_u64 v[6:7], v[244:245], 0, s[40:41]
	s_mov_b32 m0, s68
	s_nop 0
	global_load_lds_dwordx4 v[6:7], off
	v_lshl_add_u64 v[6:7], v[246:247], 0, s[40:41]
	s_mov_b32 m0, s69
	s_nop 0
	global_load_lds_dwordx4 v[6:7], off
	s_waitcnt vmcnt(8)
	s_waitcnt lgkmcnt(0)
	s_barrier
	s_waitcnt lgkmcnt(0)
	v_mfma_f32_16x16x32_bf16 v[64:67], v[140:143], v[206:209], v[64:67]
	v_mfma_f32_16x16x32_bf16 v[64:67], v[144:147], v[214:217], v[64:67]
	v_mfma_f32_16x16x32_bf16 v[60:63], v[148:151], v[206:209], v[60:63]
	v_mfma_f32_16x16x32_bf16 v[60:63], v[152:155], v[214:217], v[60:63]
	v_mfma_f32_16x16x32_bf16 v[48:51], v[140:143], v[218:221], v[48:51]
	v_mfma_f32_16x16x32_bf16 v[48:51], v[144:147], v[222:225], v[48:51]
	v_mfma_f32_16x16x32_bf16 v[44:47], v[148:151], v[218:221], v[44:47]
	v_mfma_f32_16x16x32_bf16 v[44:47], v[152:155], v[222:225], v[44:47]
	v_mfma_f32_16x16x32_bf16 v[32:35], v[140:143], v[226:229], v[32:35]
	v_mfma_f32_16x16x32_bf16 v[32:35], v[144:147], v[230:233], v[32:35]
	v_mfma_f32_16x16x32_bf16 v[28:31], v[148:151], v[226:229], v[28:31]
	v_mfma_f32_16x16x32_bf16 v[28:31], v[152:155], v[230:233], v[28:31]
	v_mfma_f32_16x16x32_bf16 v[16:19], v[140:143], v[234:237], v[16:19]
	v_mfma_f32_16x16x32_bf16 v[16:19], v[144:147], v[238:241], v[16:19]
	v_mfma_f32_16x16x32_bf16 v[12:15], v[148:151], v[234:237], v[12:15]
	v_mfma_f32_16x16x32_bf16 v[12:15], v[152:155], v[238:241], v[12:15]
	v_mfma_f32_16x16x32_bf16 v[56:59], v[190:193], v[206:209], v[56:59]
	v_mfma_f32_16x16x32_bf16 v[52:55], v[198:201], v[206:209], v[52:55]
	v_mfma_f32_16x16x32_bf16 v[40:43], v[190:193], v[218:221], v[40:43]
	v_mfma_f32_16x16x32_bf16 v[36:39], v[198:201], v[218:221], v[36:39]
	v_mfma_f32_16x16x32_bf16 v[24:27], v[190:193], v[226:229], v[24:27]
	v_mfma_f32_16x16x32_bf16 v[20:23], v[198:201], v[226:229], v[20:23]
	v_mfma_f32_16x16x32_bf16 v[6:9], v[190:193], v[234:237], v[8:11]
	v_mfma_f32_16x16x32_bf16 v[2:5], v[198:201], v[234:237], v[2:5]
	v_mfma_f32_16x16x32_bf16 v[56:59], v[194:197], v[214:217], v[56:59]
	v_mfma_f32_16x16x32_bf16 v[52:55], v[202:205], v[214:217], v[52:55]
	v_mfma_f32_16x16x32_bf16 v[40:43], v[194:197], v[222:225], v[40:43]
	v_mfma_f32_16x16x32_bf16 v[36:39], v[202:205], v[222:225], v[36:39]
	v_mfma_f32_16x16x32_bf16 v[24:27], v[194:197], v[230:233], v[24:27]
	v_mfma_f32_16x16x32_bf16 v[20:23], v[202:205], v[230:233], v[20:23]
	v_mfma_f32_16x16x32_bf16 v[8:11], v[194:197], v[238:241], v[6:9]
	v_mfma_f32_16x16x32_bf16 v[4:7], v[202:205], v[238:241], v[2:5]
	s_barrier
	s_add_i32 s75, s75, 2
	s_add_u32 s54, s54, 0x100
	s_addc_u32 s55, s55, 0
	s_cmp_gt_u32 s75, 29
	s_cbranch_scc1 .LBB0_671

; #define PG8_STAGE(bufoff, gbase, voff) do { _Pragma("unroll") for (int _i = 0; _i < 2; ++_i) \
;         __builtin_amdgcn_global_load_lds((const unsigned*)((const char*)(gbase) + (voff)[_i]), (PG8_LAS unsigned*)(lds + (bufoff) + ldsw + _i * 8192), 16, 0, 0); } while (0)
; #define PG8_WAIT_V(n) asm volatile("s_waitcnt vmcnt(" #n ")" ::: "memory")
; #define PG8_WAIT_L(n) asm volatile("s_waitcnt lgkmcnt(" #n ")" ::: "memory")
; #define PG8_BAR __builtin_amdgcn_s_barrier()
; #define PG8_SCHED __builtin_amdgcn_sched_barrier(0)
;     ...
;             PG8_LDB(B0, 0, 0); PG8_LDB(B1, 0, 1); PG8_SCHED; PG8_LDA(At, 0, 0); PG8_STAGE(PG8_SA(1, 1), a1 + hstep, voffA);
;             PG8_WAIT_V(8); PG8_WAIT_L(0); PG8_BAR; PG8_MMA(0, 0, At, B0); PG8_MMA(0, 1, At, B1); PG8_BAR; PG8_SCHED;
;             PG8_LDA(At, 0, 1); PG8_STAGE(PG8_SB(0, 0), b2, voffB); PG8_STAGE(PG8_SB(0, 1), b2 + hstep, voffB); PG8_STAGE(PG8_SA(0, 0), a2, voffA);
.LBB0_851:
	v_add_u32_e32 v157, s60, v149
	ds_read_b128 v[166:169], v157
	ds_read_b128 v[170:173], v157 offset:1024
	ds_read_b128 v[174:177], v157 offset:2048
	ds_read_b128 v[178:181], v157 offset:3072
	v_add_u32_e32 v157, s61, v149
	ds_read_b128 v[182:185], v157
	ds_read_b128 v[186:189], v157 offset:1024
	ds_read_b128 v[190:193], v157 offset:2048
	ds_read_b128 v[194:197], v157 offset:3072
	s_add_u32 s33, s42, 0xfffc0080
	s_addc_u32 s46, s43, -1
	s_and_b64 s[44:45], s[44:45], exec
	s_cselect_b32 s47, s34, s46
	s_cselect_b32 s46, s35, s33
	s_cselect_b32 s45, s25, s66
	s_cselect_b32 s44, s37, s65
	v_lshl_add_u64 v[210:211], s[42:43], 0, v[138:139]
	s_add_i32 m0, s51, 0xc000
	ds_read_b128 v[198:201], v153
	ds_read_b128 v[202:205], v153 offset:1024
	ds_read_b128 v[206:209], v153 offset:2048
	ds_read_b128 v[214:217], v153 offset:3072
	ds_read_b128 v[218:221], v153 offset:4096
	ds_read_b128 v[222:225], v153 offset:5120
	ds_read_b128 v[226:229], v153 offset:6144
	ds_read_b128 v[230:233], v153 offset:7168
	global_load_lds_dwordx4 v[210:211], off
	v_lshl_add_u64 v[210:211], s[42:43], 0, v[140:141]
	s_add_i32 m0, s51, 0xe000
	s_nop 0
	global_load_lds_dwordx4 v[210:211], off
	s_waitcnt vmcnt(8)
	s_waitcnt lgkmcnt(0)
	s_barrier
	s_waitcnt lgkmcnt(0)
	v_mfma_i32_16x16x64_i8 v[124:127], v[166:169], v[198:201], v[124:127]
	v_mfma_i32_16x16x64_i8 v[124:127], v[170:173], v[202:205], v[124:127]
	v_mfma_i32_16x16x64_i8 v[120:123], v[174:177], v[198:201], v[120:123]
	v_mfma_i32_16x16x64_i8 v[120:123], v[178:181], v[202:205], v[120:123]
	v_mfma_i32_16x16x64_i8 v[108:111], v[166:169], v[206:209], v[108:111]
	v_mfma_i32_16x16x64_i8 v[108:111], v[170:173], v[214:217], v[108:111]
	v_mfma_i32_16x16x64_i8 v[100:103], v[174:177], v[206:209], v[100:103]
	v_mfma_i32_16x16x64_i8 v[100:103], v[178:181], v[214:217], v[100:103]
	v_mfma_i32_16x16x64_i8 v[92:95], v[166:169], v[218:221], v[92:95]
	v_mfma_i32_16x16x64_i8 v[92:95], v[170:173], v[222:225], v[92:95]
	v_mfma_i32_16x16x64_i8 v[84:87], v[174:177], v[218:221], v[84:87]
	v_mfma_i32_16x16x64_i8 v[84:87], v[178:181], v[222:225], v[84:87]
	v_mfma_i32_16x16x64_i8 v[76:79], v[166:169], v[226:229], v[76:79]
	v_mfma_i32_16x16x64_i8 v[76:79], v[170:173], v[230:233], v[76:79]
	v_mfma_i32_16x16x64_i8 v[68:71], v[174:177], v[226:229], v[68:71]
	v_mfma_i32_16x16x64_i8 v[68:71], v[178:181], v[230:233], v[68:71]
	v_mfma_i32_16x16x64_i8 v[116:119], v[182:185], v[198:201], v[116:119]
	v_mfma_i32_16x16x64_i8 v[116:119], v[186:189], v[202:205], v[116:119]
	v_mfma_i32_16x16x64_i8 v[112:115], v[190:193], v[198:201], v[112:115]
	v_mfma_i32_16x16x64_i8 v[112:115], v[194:197], v[202:205], v[112:115]
	v_mfma_i32_16x16x64_i8 v[104:107], v[182:185], v[206:209], v[104:107]
	v_mfma_i32_16x16x64_i8 v[104:107], v[186:189], v[214:217], v[104:107]
	v_mfma_i32_16x16x64_i8 v[96:99], v[190:193], v[206:209], v[96:99]
	v_mfma_i32_16x16x64_i8 v[96:99], v[194:197], v[214:217], v[96:99]
	v_mfma_i32_16x16x64_i8 v[88:91], v[182:185], v[218:221], v[88:91]
	v_mfma_i32_16x16x64_i8 v[88:91], v[186:189], v[222:225], v[88:91]
	v_mfma_i32_16x16x64_i8 v[80:83], v[190:193], v[218:221], v[80:83]
	v_mfma_i32_16x16x64_i8 v[80:83], v[194:197], v[222:225], v[80:83]
	v_mfma_i32_16x16x64_i8 v[72:75], v[182:185], v[226:229], v[72:75]
	v_mfma_i32_16x16x64_i8 v[72:75], v[186:189], v[230:233], v[72:75]
	v_mfma_i32_16x16x64_i8 v[64:67], v[190:193], v[226:229], v[64:67]
	v_mfma_i32_16x16x64_i8 v[64:67], v[194:197], v[230:233], v[64:67]
	s_barrier
	s_add_i32 s33, s60, s48
	v_lshl_add_u64 v[210:211], s[44:45], 0, v[132:133]
	s_mov_b32 m0, s33
	ds_read_b128 v[198:201], v153 offset:16384
	ds_read_b128 v[202:205], v153 offset:17408
	ds_read_b128 v[206:209], v153 offset:18432
	ds_read_b128 v[214:217], v153 offset:19456
	ds_read_b128 v[218:221], v153 offset:20480
	ds_read_b128 v[222:225], v153 offset:21504
	ds_read_b128 v[226:229], v153 offset:22528
	ds_read_b128 v[230:233], v153 offset:23552
	global_load_lds_dwordx4 v[210:211], off
	s_add_i32 m0, s33, 0x2000
	s_add_u32 s68, s44, 0x40000
	v_lshl_add_u64 v[234:235], s[44:45], 0, v[128:129]
	s_addc_u32 s69, s45, 0
	s_add_i32 s33, s61, s48
	global_load_lds_dwordx4 v[234:235], off
	v_lshl_add_u64 v[236:237], s[68:69], 0, v[132:133]
	s_mov_b32 m0, s33
	v_lshl_add_u64 v[238:239], s[46:47], 0, v[130:131]
	global_load_lds_dwordx4 v[236:237], off
	v_lshl_add_u64 v[236:237], s[68:69], 0, v[128:129]
	s_add_i32 m0, s33, 0x2000
	s_nop 0
	global_load_lds_dwordx4 v[236:237], off
	v_lshl_add_u64 v[236:237], s[46:47], 0, v[134:135]
	s_mov_b32 m0, s51
	s_nop 0
	global_load_lds_dwordx4 v[236:237], off
	s_mov_b32 m0, s52
	s_nop 0
	global_load_lds_dwordx4 v[238:239], off
	s_waitcnt vmcnt(8)
	s_waitcnt lgkmcnt(0)
	s_barrier
; #define PG8_STAGE(bufoff, gbase, voff) do { _Pragma("unroll") for (int _i = 0; _i < 2; ++_i) \
;         __builtin_amdgcn_global_load_lds((const unsigned*)((const char*)(gbase) + (voff)[_i]), (PG8_LAS unsigned*)(lds + (bufoff) + ldsw + _i * 8192), 16, 0, 0); } while (0)
; #define PG8_WAIT_V(n) asm volatile("s_waitcnt vmcnt(" #n ")" ::: "memory")
; #define PG8_WAIT_L(n) asm volatile("s_waitcnt lgkmcnt(" #n ")" ::: "memory")
; #define PG8_BAR __builtin_amdgcn_s_barrier()
; #define PG8_SCHED __builtin_amdgcn_sched_barrier(0)
;     ...
;             PG8_WAIT_V(8); PG8_WAIT_L(0); PG8_BAR; PG8_MMA(1, 0, At, B0); PG8_MMA(1, 1, At, B1); PG8_BAR; PG8_SCHED;
;             PG8_LDB(B0, 1, 0); PG8_LDB(B1, 1, 1); PG8_SCHED; PG8_LDA(At, 1, 0); PG8_STAGE(PG8_SA(0, 1), a2 + hstep, voffA);
;             PG8_WAIT_V(8); PG8_WAIT_L(0); PG8_BAR; PG8_MMA(0, 0, At, B0); PG8_MMA(0, 1, At, B1); PG8_BAR; PG8_SCHED;
	s_waitcnt lgkmcnt(0)
	v_mfma_i32_16x16x64_i8 v[60:63], v[166:169], v[198:201], v[60:63]
	v_mfma_i32_16x16x64_i8 v[60:63], v[170:173], v[202:205], v[60:63]
	v_mfma_i32_16x16x64_i8 v[52:55], v[174:177], v[198:201], v[52:55]
	v_mfma_i32_16x16x64_i8 v[52:55], v[178:181], v[202:205], v[52:55]
	v_mfma_i32_16x16x64_i8 v[44:47], v[166:169], v[206:209], v[44:47]
	v_mfma_i32_16x16x64_i8 v[44:47], v[170:173], v[214:217], v[44:47]
	v_mfma_i32_16x16x64_i8 v[36:39], v[174:177], v[206:209], v[36:39]
	v_mfma_i32_16x16x64_i8 v[36:39], v[178:181], v[214:217], v[36:39]
	v_mfma_i32_16x16x64_i8 v[28:31], v[166:169], v[218:221], v[28:31]
	v_mfma_i32_16x16x64_i8 v[28:31], v[170:173], v[222:225], v[28:31]
	v_mfma_i32_16x16x64_i8 v[20:23], v[174:177], v[218:221], v[20:23]
	v_mfma_i32_16x16x64_i8 v[20:23], v[178:181], v[222:225], v[20:23]
	v_mfma_i32_16x16x64_i8 v[12:15], v[166:169], v[226:229], v[12:15]
	v_mfma_i32_16x16x64_i8 v[12:15], v[170:173], v[230:233], v[12:15]
	v_mfma_i32_16x16x64_i8 v[4:7], v[174:177], v[226:229], v[4:7]
	v_mfma_i32_16x16x64_i8 v[4:7], v[178:181], v[230:233], v[4:7]
	v_mfma_i32_16x16x64_i8 v[56:59], v[182:185], v[198:201], v[56:59]
	v_mfma_i32_16x16x64_i8 v[56:59], v[186:189], v[202:205], v[56:59]
	v_mfma_i32_16x16x64_i8 v[48:51], v[190:193], v[198:201], v[48:51]
	v_mfma_i32_16x16x64_i8 v[48:51], v[194:197], v[202:205], v[48:51]
	v_mfma_i32_16x16x64_i8 v[40:43], v[182:185], v[206:209], v[40:43]
	v_mfma_i32_16x16x64_i8 v[40:43], v[186:189], v[214:217], v[40:43]
	v_mfma_i32_16x16x64_i8 v[32:35], v[190:193], v[206:209], v[32:35]
	v_mfma_i32_16x16x64_i8 v[32:35], v[194:197], v[214:217], v[32:35]
	v_mfma_i32_16x16x64_i8 v[24:27], v[182:185], v[218:221], v[24:27]
	v_mfma_i32_16x16x64_i8 v[24:27], v[186:189], v[222:225], v[24:27]
	v_mfma_i32_16x16x64_i8 v[16:19], v[190:193], v[218:221], v[16:19]
	v_mfma_i32_16x16x64_i8 v[16:19], v[194:197], v[222:225], v[16:19]
	v_mfma_i32_16x16x64_i8 v[8:11], v[182:185], v[226:229], v[8:11]
	v_mfma_i32_16x16x64_i8 v[8:11], v[186:189], v[230:233], v[8:11]
	v_mfma_i32_16x16x64_i8 v[0:3], v[190:193], v[226:229], v[0:3]
	v_mfma_i32_16x16x64_i8 v[0:3], v[194:197], v[230:233], v[0:3]
	s_barrier
	s_add_i32 s33, 0, 0x18000
	v_add_u32_e32 v157, s33, v149
	s_add_i32 s68, 0, 0x1c000
	ds_read_b128 v[166:169], v157
	ds_read_b128 v[170:173], v157 offset:1024
	ds_read_b128 v[174:177], v157 offset:2048
	ds_read_b128 v[178:181], v157 offset:3072
	v_add_u32_e32 v157, s68, v149
	ds_read_b128 v[182:185], v157
	ds_read_b128 v[186:189], v157 offset:1024
	ds_read_b128 v[190:193], v157 offset:2048
	ds_read_b128 v[194:197], v157 offset:3072
	s_add_u32 s46, s46, 0x40000
	s_addc_u32 s47, s47, 0
	s_mov_b32 m0, s53
	v_lshl_add_u64 v[240:241], s[46:47], 0, v[134:135]
	ds_read_b128 v[198:201], v153 offset:32768
	ds_read_b128 v[202:205], v153 offset:33792
	ds_read_b128 v[206:209], v153 offset:34816
	ds_read_b128 v[214:217], v153 offset:35840
	ds_read_b128 v[218:221], v153 offset:36864
	ds_read_b128 v[222:225], v153 offset:37888
	ds_read_b128 v[226:229], v153 offset:38912
	ds_read_b128 v[230:233], v153 offset:39936
	global_load_lds_dwordx4 v[240:241], off
	v_lshl_add_u64 v[240:241], s[46:47], 0, v[130:131]
	s_mov_b32 m0, s54
	s_nop 0
	global_load_lds_dwordx4 v[240:241], off
	s_waitcnt vmcnt(8)
	s_waitcnt lgkmcnt(0)
	s_barrier
	s_waitcnt lgkmcnt(0)
	v_mfma_i32_16x16x64_i8 v[124:127], v[166:169], v[198:201], v[124:127]
	v_mfma_i32_16x16x64_i8 v[124:127], v[170:173], v[202:205], v[124:127]
	v_mfma_i32_16x16x64_i8 v[120:123], v[174:177], v[198:201], v[120:123]
	v_mfma_i32_16x16x64_i8 v[120:123], v[178:181], v[202:205], v[120:123]
	v_mfma_i32_16x16x64_i8 v[108:111], v[166:169], v[206:209], v[108:111]
	v_mfma_i32_16x16x64_i8 v[108:111], v[170:173], v[214:217], v[108:111]
	v_mfma_i32_16x16x64_i8 v[100:103], v[174:177], v[206:209], v[100:103]
	v_mfma_i32_16x16x64_i8 v[100:103], v[178:181], v[214:217], v[100:103]
	v_mfma_i32_16x16x64_i8 v[92:95], v[166:169], v[218:221], v[92:95]
	v_mfma_i32_16x16x64_i8 v[92:95], v[170:173], v[222:225], v[92:95]
	v_mfma_i32_16x16x64_i8 v[84:87], v[174:177], v[218:221], v[84:87]
	v_mfma_i32_16x16x64_i8 v[84:87], v[178:181], v[222:225], v[84:87]
	v_mfma_i32_16x16x64_i8 v[76:79], v[166:169], v[226:229], v[76:79]
	v_mfma_i32_16x16x64_i8 v[76:79], v[170:173], v[230:233], v[76:79]
	v_mfma_i32_16x16x64_i8 v[68:71], v[174:177], v[226:229], v[68:71]
	v_mfma_i32_16x16x64_i8 v[68:71], v[178:181], v[230:233], v[68:71]
	v_mfma_i32_16x16x64_i8 v[116:119], v[182:185], v[198:201], v[116:119]
	v_mfma_i32_16x16x64_i8 v[116:119], v[186:189], v[202:205], v[116:119]
	v_mfma_i32_16x16x64_i8 v[112:115], v[190:193], v[198:201], v[112:115]
	v_mfma_i32_16x16x64_i8 v[112:115], v[194:197], v[202:205], v[112:115]
	v_mfma_i32_16x16x64_i8 v[104:107], v[182:185], v[206:209], v[104:107]
	v_mfma_i32_16x16x64_i8 v[104:107], v[186:189], v[214:217], v[104:107]
	v_mfma_i32_16x16x64_i8 v[96:99], v[190:193], v[206:209], v[96:99]
	v_mfma_i32_16x16x64_i8 v[96:99], v[194:197], v[214:217], v[96:99]
	v_mfma_i32_16x16x64_i8 v[88:91], v[182:185], v[218:221], v[88:91]
	v_mfma_i32_16x16x64_i8 v[88:91], v[186:189], v[222:225], v[88:91]
	v_mfma_i32_16x16x64_i8 v[80:83], v[190:193], v[218:221], v[80:83]
	v_mfma_i32_16x16x64_i8 v[80:83], v[194:197], v[222:225], v[80:83]
	v_mfma_i32_16x16x64_i8 v[72:75], v[182:185], v[226:229], v[72:75]
	v_mfma_i32_16x16x64_i8 v[72:75], v[186:189], v[230:233], v[72:75]
	v_mfma_i32_16x16x64_i8 v[64:67], v[190:193], v[226:229], v[64:67]
	v_mfma_i32_16x16x64_i8 v[64:67], v[194:197], v[230:233], v[64:67]
	s_barrier
; #define PG8_STAGE(bufoff, gbase, voff) do { _Pragma("unroll") for (int _i = 0; _i < 2; ++_i) \
;         __builtin_amdgcn_global_load_lds((const unsigned*)((const char*)(gbase) + (voff)[_i]), (PG8_LAS unsigned*)(lds + (bufoff) + ldsw + _i * 8192), 16, 0, 0); } while (0)
; #define PG8_WAIT_V(n) asm volatile("s_waitcnt vmcnt(" #n ")" ::: "memory")
; #define PG8_WAIT_L(n) asm volatile("s_waitcnt lgkmcnt(" #n ")" ::: "memory")
; #define PG8_BAR __builtin_amdgcn_s_barrier()
; #define PG8_SCHED __builtin_amdgcn_sched_barrier(0)
;     ...
;         for (int t = 0; t < nt; t += 2) {
;     ...
;             PG8_LDA(At, 1, 1); PG8_STAGE(PG8_SB(1, 0), b3, voffB); PG8_STAGE(PG8_SB(1, 1), b3 + hstep, voffB); PG8_STAGE(PG8_SA(1, 0), a3, voffA);
;             PG8_WAIT_V(8); PG8_WAIT_L(0); PG8_BAR; PG8_MMA(1, 0, At, B0); PG8_MMA(1, 1, At, B1); PG8_BAR; PG8_SCHED;
	s_add_i32 s33, s33, s48
	v_lshl_add_u64 v[210:211], v[210:211], 0, s[10:11]
	s_mov_b32 m0, s33
	ds_read_b128 v[198:201], v153 offset:49152
	ds_read_b128 v[202:205], v153 offset:50176
	ds_read_b128 v[206:209], v153 offset:51200
	ds_read_b128 v[214:217], v153 offset:52224
	ds_read_b128 v[218:221], v153 offset:53248
	ds_read_b128 v[222:225], v153 offset:54272
	ds_read_b128 v[226:229], v153 offset:55296
	ds_read_b128 v[230:233], v153 offset:56320
	global_load_lds_dwordx4 v[210:211], off
	s_add_i32 m0, s33, 0x2000
	s_add_u32 s44, s44, 0x40080
	v_lshl_add_u64 v[210:211], v[234:235], 0, s[10:11]
	s_addc_u32 s45, s45, 0
	s_add_i32 s33, s68, s48
	global_load_lds_dwordx4 v[210:211], off
	v_lshl_add_u64 v[210:211], s[44:45], 0, v[132:133]
	s_mov_b32 m0, s33
	s_nop 0
	global_load_lds_dwordx4 v[210:211], off
	v_lshl_add_u64 v[210:211], s[44:45], 0, v[128:129]
	s_add_i32 m0, s33, 0x2000
	s_nop 0
	global_load_lds_dwordx4 v[210:211], off
	v_lshl_add_u64 v[210:211], v[236:237], 0, s[10:11]
	s_mov_b32 m0, s56
	s_nop 0
	global_load_lds_dwordx4 v[210:211], off
	v_lshl_add_u64 v[210:211], v[238:239], 0, s[10:11]
	s_mov_b32 m0, s57
	s_nop 0
	global_load_lds_dwordx4 v[210:211], off
	s_waitcnt vmcnt(8)
	s_waitcnt lgkmcnt(0)
	s_barrier
	s_waitcnt lgkmcnt(0)
	v_mfma_i32_16x16x64_i8 v[60:63], v[166:169], v[198:201], v[60:63]
	v_mfma_i32_16x16x64_i8 v[60:63], v[170:173], v[202:205], v[60:63]
	v_mfma_i32_16x16x64_i8 v[52:55], v[174:177], v[198:201], v[52:55]
	v_mfma_i32_16x16x64_i8 v[52:55], v[178:181], v[202:205], v[52:55]
	v_mfma_i32_16x16x64_i8 v[44:47], v[166:169], v[206:209], v[44:47]
	v_mfma_i32_16x16x64_i8 v[44:47], v[170:173], v[214:217], v[44:47]
	v_mfma_i32_16x16x64_i8 v[36:39], v[174:177], v[206:209], v[36:39]
	v_mfma_i32_16x16x64_i8 v[36:39], v[178:181], v[214:217], v[36:39]
	v_mfma_i32_16x16x64_i8 v[28:31], v[166:169], v[218:221], v[28:31]
	v_mfma_i32_16x16x64_i8 v[28:31], v[170:173], v[222:225], v[28:31]
	v_mfma_i32_16x16x64_i8 v[20:23], v[174:177], v[218:221], v[20:23]
	v_mfma_i32_16x16x64_i8 v[20:23], v[178:181], v[222:225], v[20:23]
	v_mfma_i32_16x16x64_i8 v[12:15], v[166:169], v[226:229], v[12:15]
	v_mfma_i32_16x16x64_i8 v[12:15], v[170:173], v[230:233], v[12:15]
	v_mfma_i32_16x16x64_i8 v[4:7], v[174:177], v[226:229], v[4:7]
	v_mfma_i32_16x16x64_i8 v[4:7], v[178:181], v[230:233], v[4:7]
	v_mfma_i32_16x16x64_i8 v[56:59], v[182:185], v[198:201], v[56:59]
	v_mfma_i32_16x16x64_i8 v[56:59], v[186:189], v[202:205], v[56:59]
	v_mfma_i32_16x16x64_i8 v[48:51], v[190:193], v[198:201], v[48:51]
	v_mfma_i32_16x16x64_i8 v[48:51], v[194:197], v[202:205], v[48:51]
	v_mfma_i32_16x16x64_i8 v[40:43], v[182:185], v[206:209], v[40:43]
	v_mfma_i32_16x16x64_i8 v[40:43], v[186:189], v[214:217], v[40:43]
	v_mfma_i32_16x16x64_i8 v[32:35], v[190:193], v[206:209], v[32:35]
	v_mfma_i32_16x16x64_i8 v[32:35], v[194:197], v[214:217], v[32:35]
	v_mfma_i32_16x16x64_i8 v[24:27], v[182:185], v[218:221], v[24:27]
	v_mfma_i32_16x16x64_i8 v[24:27], v[186:189], v[222:225], v[24:27]
	v_mfma_i32_16x16x64_i8 v[16:19], v[190:193], v[218:221], v[16:19]
	v_mfma_i32_16x16x64_i8 v[16:19], v[194:197], v[222:225], v[16:19]
	v_mfma_i32_16x16x64_i8 v[8:11], v[182:185], v[226:229], v[8:11]
	v_mfma_i32_16x16x64_i8 v[8:11], v[186:189], v[230:233], v[8:11]
	v_mfma_i32_16x16x64_i8 v[0:3], v[190:193], v[226:229], v[0:3]
	v_mfma_i32_16x16x64_i8 v[0:3], v[194:197], v[230:233], v[0:3]
	s_barrier
	s_add_i32 s67, s67, 2
	s_add_u32 s42, s42, 0x100
	s_addc_u32 s43, s43, 0
	s_add_u32 s65, s65, 0x100
	s_addc_u32 s66, s66, 0
	s_cmp_gt_u32 s67, 13
	s_cbranch_scc1 .LBB0_854

; #define PG8_STAGE(bufoff, gbase, voff) do { _Pragma("unroll") for (int _i = 0; _i < 2; ++_i) \
;         __builtin_amdgcn_global_load_lds((const unsigned*)((const char*)(gbase) + (voff)[_i]), (PG8_LAS unsigned*)(lds + (bufoff) + ldsw + _i * 8192), 16, 0, 0); } while (0)
; #define PG8_WAIT_V(n) asm volatile("s_waitcnt vmcnt(" #n ")" ::: "memory")
; #define PG8_WAIT_L(n) asm volatile("s_waitcnt lgkmcnt(" #n ")" ::: "memory")
; #define PG8_BAR __builtin_amdgcn_s_barrier()
; #define PG8_SCHED __builtin_amdgcn_sched_barrier(0)
;     ...
;             PG8_LDB(B0, 0, 0); PG8_LDB(B1, 0, 1); PG8_SCHED; PG8_LDA(At, 0, 0); PG8_STAGE(PG8_SA(1, 1), a1 + hstep, voffA);
;             PG8_WAIT_V(8); PG8_WAIT_L(0); PG8_BAR; PG8_MMA(0, 0, At, B0); PG8_MMA(0, 1, At, B1); PG8_BAR; PG8_SCHED;
;             PG8_LDA(At, 0, 1); PG8_STAGE(PG8_SB(0, 0), b2, voffB); PG8_STAGE(PG8_SB(0, 1), b2 + hstep, voffB); PG8_STAGE(PG8_SA(0, 0), a2, voffA);
;             PG8_WAIT_V(8); PG8_WAIT_L(0); PG8_BAR; PG8_MMA(1, 0, At, B0); PG8_MMA(1, 1, At, B1); PG8_BAR; PG8_SCHED;
.LBB0_936:
	ds_read_b128 v[16:19], v187
	ds_read_b128 v[20:23], v187 offset:16
	ds_read_b128 v[24:27], v187 offset:2048
	ds_read_b128 v[28:31], v187 offset:2064
	ds_read_b128 v[0:3], v188
	ds_read_b128 v[4:7], v188 offset:16
	ds_read_b128 v[8:11], v188 offset:2048
	ds_read_b128 v[12:15], v188 offset:2064
	s_add_u32 s24, s20, 0xfff50080
	s_addc_u32 s25, s21, -1
	s_cmp_eq_u32 s48, 40
	s_cselect_b32 s29, s5, s25
	s_cselect_b32 s28, s4, s24
	s_cselect_b32 s25, s19, s47
	s_cselect_b32 s24, s18, s46
	v_lshl_add_u64 v[214:215], s[20:21], 0, v[168:169]
	s_add_i32 m0, s31, 0xc000
	ds_read_b128 v[176:179], v189
	ds_read_b128 v[180:183], v189 offset:16
	ds_read_b128 v[190:193], v189 offset:2048
	ds_read_b128 v[194:197], v189 offset:2064
	ds_read_b128 v[198:201], v189 offset:4096
	ds_read_b128 v[202:205], v189 offset:4112
	ds_read_b128 v[206:209], v189 offset:6144
	ds_read_b128 v[210:213], v189 offset:6160
	global_load_lds_dwordx4 v[214:215], off
	v_lshl_add_u64 v[214:215], s[20:21], 0, v[170:171]
	s_add_i32 m0, s31, 0xe000
	s_nop 0
	global_load_lds_dwordx4 v[214:215], off
	s_waitcnt vmcnt(8)
	s_waitcnt lgkmcnt(0)
	s_barrier
	s_waitcnt lgkmcnt(0)
	v_mfma_f32_16x16x128_f8f6f4 v[156:159], v[16:23], v[176:183], v[156:159]
	v_mfma_f32_16x16x128_f8f6f4 v[152:155], v[24:31], v[176:183], v[152:155]
	v_mfma_f32_16x16x128_f8f6f4 v[148:151], v[16:23], v[190:197], v[148:151]
	v_mfma_f32_16x16x128_f8f6f4 v[144:147], v[24:31], v[190:197], v[144:147]
	v_mfma_f32_16x16x128_f8f6f4 v[128:131], v[16:23], v[198:205], v[128:131]
	v_mfma_f32_16x16x128_f8f6f4 v[120:123], v[24:31], v[198:205], v[120:123]
	v_mfma_f32_16x16x128_f8f6f4 v[112:115], v[16:23], v[206:213], v[112:115]
	v_mfma_f32_16x16x128_f8f6f4 v[104:107], v[24:31], v[206:213], v[104:107]
	v_mfma_f32_16x16x128_f8f6f4 v[140:143], v[0:7], v[176:183], v[140:143]
	v_mfma_f32_16x16x128_f8f6f4 v[136:139], v[8:15], v[176:183], v[136:139]
	v_mfma_f32_16x16x128_f8f6f4 v[132:135], v[0:7], v[190:197], v[132:135]
	v_mfma_f32_16x16x128_f8f6f4 v[124:127], v[8:15], v[190:197], v[124:127]
	v_mfma_f32_16x16x128_f8f6f4 v[116:119], v[0:7], v[198:205], v[116:119]
	v_mfma_f32_16x16x128_f8f6f4 v[108:111], v[8:15], v[198:205], v[108:111]
	v_mfma_f32_16x16x128_f8f6f4 v[100:103], v[0:7], v[206:213], v[100:103]
	v_mfma_f32_16x16x128_f8f6f4 v[96:99], v[8:15], v[206:213], v[96:99]
	s_barrier
	s_add_i32 s49, s40, s30
	v_lshl_add_u64 v[176:177], s[24:25], 0, v[162:163]
	s_mov_b32 m0, s49
	ds_read_b128 v[190:193], v189 offset:16384
	ds_read_b128 v[194:197], v189 offset:16400
	ds_read_b128 v[198:201], v189 offset:18432
	ds_read_b128 v[202:205], v189 offset:18448
	ds_read_b128 v[206:209], v189 offset:20480
	ds_read_b128 v[210:213], v189 offset:20496
	ds_read_b128 v[214:217], v189 offset:22528
	ds_read_b128 v[218:221], v189 offset:22544
	global_load_lds_dwordx4 v[176:177], off
	s_add_i32 m0, s49, 0x2000
	s_add_u32 s50, s24, 0xb0000
	v_lshl_add_u64 v[178:179], s[24:25], 0, v[166:167]
	s_addc_u32 s51, s25, 0
	s_add_i32 s49, s41, s30
	global_load_lds_dwordx4 v[178:179], off
	v_lshl_add_u64 v[180:181], s[50:51], 0, v[162:163]
	s_mov_b32 m0, s49
	v_lshl_add_u64 v[182:183], s[28:29], 0, v[164:165]
	global_load_lds_dwordx4 v[180:181], off
	v_lshl_add_u64 v[180:181], s[50:51], 0, v[166:167]
	s_add_i32 m0, s49, 0x2000
	s_nop 0
	global_load_lds_dwordx4 v[180:181], off
	v_lshl_add_u64 v[180:181], s[28:29], 0, v[160:161]
	s_mov_b32 m0, s31
	s_nop 0
	global_load_lds_dwordx4 v[180:181], off
	s_mov_b32 m0, s33
	s_nop 0
	global_load_lds_dwordx4 v[182:183], off
	s_waitcnt vmcnt(8)
	s_waitcnt lgkmcnt(0)
	s_barrier
	s_waitcnt lgkmcnt(0)
	v_mfma_f32_16x16x128_f8f6f4 v[92:95], v[16:23], v[190:197], v[92:95]
	v_mfma_f32_16x16x128_f8f6f4 v[88:91], v[24:31], v[190:197], v[88:91]
	v_mfma_f32_16x16x128_f8f6f4 v[80:83], v[16:23], v[198:205], v[80:83]
	v_mfma_f32_16x16x128_f8f6f4 v[72:75], v[24:31], v[198:205], v[72:75]
	v_mfma_f32_16x16x128_f8f6f4 v[64:67], v[16:23], v[206:213], v[64:67]
	v_mfma_f32_16x16x128_f8f6f4 v[56:59], v[24:31], v[206:213], v[56:59]
	v_mfma_f32_16x16x128_f8f6f4 v[48:51], v[16:23], v[214:221], v[48:51]
	v_mfma_f32_16x16x128_f8f6f4 v[40:43], v[24:31], v[214:221], v[40:43]
	v_mfma_f32_16x16x128_f8f6f4 v[84:87], v[0:7], v[190:197], v[84:87]
	v_mfma_f32_16x16x128_f8f6f4 v[76:79], v[8:15], v[190:197], v[76:79]
	v_mfma_f32_16x16x128_f8f6f4 v[68:71], v[0:7], v[198:205], v[68:71]
	v_mfma_f32_16x16x128_f8f6f4 v[60:63], v[8:15], v[198:205], v[60:63]
	v_mfma_f32_16x16x128_f8f6f4 v[52:55], v[0:7], v[206:213], v[52:55]
	v_mfma_f32_16x16x128_f8f6f4 v[44:47], v[8:15], v[206:213], v[44:47]
	v_mfma_f32_16x16x128_f8f6f4 v[36:39], v[0:7], v[214:221], v[36:39]
	v_mfma_f32_16x16x128_f8f6f4 v[32:35], v[8:15], v[214:221], v[32:35]
	s_barrier
; #define PG8_STAGE(bufoff, gbase, voff) do { _Pragma("unroll") for (int _i = 0; _i < 2; ++_i) \
;         __builtin_amdgcn_global_load_lds((const unsigned*)((const char*)(gbase) + (voff)[_i]), (PG8_LAS unsigned*)(lds + (bufoff) + ldsw + _i * 8192), 16, 0, 0); } while (0)
; #define PG8_WAIT_V(n) asm volatile("s_waitcnt vmcnt(" #n ")" ::: "memory")
; #define PG8_WAIT_L(n) asm volatile("s_waitcnt lgkmcnt(" #n ")" ::: "memory")
; #define PG8_BAR __builtin_amdgcn_s_barrier()
; #define PG8_SCHED __builtin_amdgcn_sched_barrier(0)
;     ...
;             PG8_LDB(B0, 1, 0); PG8_LDB(B1, 1, 1); PG8_SCHED; PG8_LDA(At, 1, 0); PG8_STAGE(PG8_SA(0, 1), a2 + hstep, voffA);
;             PG8_WAIT_V(8); PG8_WAIT_L(0); PG8_BAR; PG8_MMA(0, 0, At, B0); PG8_MMA(0, 1, At, B1); PG8_BAR; PG8_SCHED;
;             PG8_LDA(At, 1, 1); PG8_STAGE(PG8_SB(1, 0), b3, voffB); PG8_STAGE(PG8_SB(1, 1), b3 + hstep, voffB); PG8_STAGE(PG8_SA(1, 0), a3, voffA);
;             PG8_WAIT_V(8); PG8_WAIT_L(0); PG8_BAR; PG8_MMA(1, 0, At, B0); PG8_MMA(1, 1, At, B1); PG8_BAR; PG8_SCHED;
;     ...
;         if constexpr (F8) asm volatile("s_nop 15\n\ts_nop 15" ::: "memory");
;         if constexpr (ALIGN_EPI) { if (wr == 0) PG8_BAR; }
	s_add_i32 s49, 0, 0x18000
	s_add_i32 s50, 0, 0x1c000
	v_add_u32_e32 v12, s49, v185
	v_add_u32_e32 v28, s50, v185
	ds_read_b128 v[0:3], v12
	ds_read_b128 v[4:7], v12 offset:16
	ds_read_b128 v[8:11], v12 offset:2048
	ds_read_b128 v[12:15], v12 offset:2064
	ds_read_b128 v[16:19], v28
	ds_read_b128 v[20:23], v28 offset:16
	ds_read_b128 v[24:27], v28 offset:2048
	ds_read_b128 v[28:31], v28 offset:2064
	s_add_u32 s28, s28, 0xb0000
	s_addc_u32 s29, s29, 0
	s_mov_b32 m0, s34
	v_lshl_add_u64 v[222:223], s[28:29], 0, v[160:161]
	ds_read_b128 v[190:193], v189 offset:32768
	ds_read_b128 v[194:197], v189 offset:32784
	ds_read_b128 v[198:201], v189 offset:34816
	ds_read_b128 v[202:205], v189 offset:34832
	ds_read_b128 v[206:209], v189 offset:36864
	ds_read_b128 v[210:213], v189 offset:36880
	ds_read_b128 v[214:217], v189 offset:38912
	ds_read_b128 v[218:221], v189 offset:38928
	global_load_lds_dwordx4 v[222:223], off
	v_lshl_add_u64 v[222:223], s[28:29], 0, v[164:165]
	s_mov_b32 m0, s35
	s_nop 0
	global_load_lds_dwordx4 v[222:223], off
	s_waitcnt vmcnt(8)
	s_waitcnt lgkmcnt(0)
	s_barrier
	s_waitcnt lgkmcnt(0)
	v_mfma_f32_16x16x128_f8f6f4 v[156:159], v[0:7], v[190:197], v[156:159]
	v_mfma_f32_16x16x128_f8f6f4 v[152:155], v[8:15], v[190:197], v[152:155]
	v_mfma_f32_16x16x128_f8f6f4 v[148:151], v[0:7], v[198:205], v[148:151]
	v_mfma_f32_16x16x128_f8f6f4 v[144:147], v[8:15], v[198:205], v[144:147]
	v_mfma_f32_16x16x128_f8f6f4 v[128:131], v[0:7], v[206:213], v[128:131]
	v_mfma_f32_16x16x128_f8f6f4 v[120:123], v[8:15], v[206:213], v[120:123]
	v_mfma_f32_16x16x128_f8f6f4 v[112:115], v[0:7], v[214:221], v[112:115]
	v_mfma_f32_16x16x128_f8f6f4 v[104:107], v[8:15], v[214:221], v[104:107]
	v_mfma_f32_16x16x128_f8f6f4 v[140:143], v[16:23], v[190:197], v[140:143]
	v_mfma_f32_16x16x128_f8f6f4 v[136:139], v[24:31], v[190:197], v[136:139]
	v_mfma_f32_16x16x128_f8f6f4 v[132:135], v[16:23], v[198:205], v[132:135]
	v_mfma_f32_16x16x128_f8f6f4 v[124:127], v[24:31], v[198:205], v[124:127]
	v_mfma_f32_16x16x128_f8f6f4 v[116:119], v[16:23], v[206:213], v[116:119]
	v_mfma_f32_16x16x128_f8f6f4 v[108:111], v[24:31], v[206:213], v[108:111]
	v_mfma_f32_16x16x128_f8f6f4 v[100:103], v[16:23], v[214:221], v[100:103]
	v_mfma_f32_16x16x128_f8f6f4 v[96:99], v[24:31], v[214:221], v[96:99]
	s_barrier
	s_add_i32 s28, s49, s30
	v_lshl_add_u64 v[176:177], v[176:177], 0, s[8:9]
	s_mov_b32 m0, s28
	ds_read_b128 v[190:193], v189 offset:49152
	ds_read_b128 v[194:197], v189 offset:49168
	ds_read_b128 v[198:201], v189 offset:51200
	ds_read_b128 v[202:205], v189 offset:51216
	ds_read_b128 v[206:209], v189 offset:53248
	ds_read_b128 v[210:213], v189 offset:53264
	ds_read_b128 v[214:217], v189 offset:55296
	ds_read_b128 v[218:221], v189 offset:55312
	global_load_lds_dwordx4 v[176:177], off
	s_add_i32 m0, s28, 0x2000
	s_add_u32 s24, s24, 0xb0080
	v_lshl_add_u64 v[176:177], v[178:179], 0, s[8:9]
	s_addc_u32 s25, s25, 0
	s_add_i32 s28, s50, s30
	global_load_lds_dwordx4 v[176:177], off
	v_lshl_add_u64 v[176:177], s[24:25], 0, v[162:163]
	s_mov_b32 m0, s28
	s_nop 0
	global_load_lds_dwordx4 v[176:177], off
	v_lshl_add_u64 v[176:177], s[24:25], 0, v[166:167]
	s_add_i32 m0, s28, 0x2000
	s_nop 0
	global_load_lds_dwordx4 v[176:177], off
	v_lshl_add_u64 v[176:177], v[180:181], 0, s[8:9]
	s_mov_b32 m0, s37
	s_nop 0
	global_load_lds_dwordx4 v[176:177], off
	v_lshl_add_u64 v[176:177], v[182:183], 0, s[8:9]
	s_mov_b32 m0, s38
	s_nop 0
	global_load_lds_dwordx4 v[176:177], off
	s_waitcnt vmcnt(8)
	s_waitcnt lgkmcnt(0)
	s_barrier
	s_waitcnt lgkmcnt(0)
	v_mfma_f32_16x16x128_f8f6f4 v[92:95], v[0:7], v[190:197], v[92:95]
	v_mfma_f32_16x16x128_f8f6f4 v[88:91], v[8:15], v[190:197], v[88:91]
	v_mfma_f32_16x16x128_f8f6f4 v[80:83], v[0:7], v[198:205], v[80:83]
	v_mfma_f32_16x16x128_f8f6f4 v[72:75], v[8:15], v[198:205], v[72:75]
	v_mfma_f32_16x16x128_f8f6f4 v[64:67], v[0:7], v[206:213], v[64:67]
	v_mfma_f32_16x16x128_f8f6f4 v[56:59], v[8:15], v[206:213], v[56:59]
	v_mfma_f32_16x16x128_f8f6f4 v[48:51], v[0:7], v[214:221], v[48:51]
	v_mfma_f32_16x16x128_f8f6f4 v[40:43], v[8:15], v[214:221], v[40:43]
	v_mfma_f32_16x16x128_f8f6f4 v[84:87], v[16:23], v[190:197], v[84:87]
	v_mfma_f32_16x16x128_f8f6f4 v[76:79], v[24:31], v[190:197], v[76:79]
	v_mfma_f32_16x16x128_f8f6f4 v[68:71], v[16:23], v[198:205], v[68:71]
	v_mfma_f32_16x16x128_f8f6f4 v[60:63], v[24:31], v[198:205], v[60:63]
	v_mfma_f32_16x16x128_f8f6f4 v[52:55], v[16:23], v[206:213], v[52:55]
	v_mfma_f32_16x16x128_f8f6f4 v[44:47], v[24:31], v[206:213], v[44:47]
	v_mfma_f32_16x16x128_f8f6f4 v[36:39], v[16:23], v[214:221], v[36:39]
	v_mfma_f32_16x16x128_f8f6f4 v[32:35], v[24:31], v[214:221], v[32:35]
	s_barrier
	s_add_i32 s48, s48, 2
	s_add_u32 s20, s20, 0x100
	s_addc_u32 s21, s21, 0
	s_add_u32 s46, s46, 0x100
	s_addc_u32 s47, s47, 0
	s_cmp_gt_u32 s48, 41
	s_cbranch_scc0 .LBB0_936
	s_nop 15
	s_nop 15
	s_and_b64 vcc, exec, s[10:11]
	s_cbranch_vccz .LBB0_939
	s_barrier
